# RG-LRU gate matmul moved to f32 MFMA (v_mfma_f32_16x16x4_f32), per-wave 32x16 output tiles; mixer jobs re-paired
# speedup vs baseline: 1.0125x; 1.0125x over previous
; __device__ __forceinline__ const float* argf(int i) { return (const float*)kargs()[i]; }
; __device__ __forceinline__ rsrc_t mk_rsrc(const void* p) { return __builtin_amdgcn_make_buffer_rsrc((void*)p, 0, 0x7fffffff, 0x00020000); }
; __device__ __forceinline__ void lru_job(const bf16_t* P, bf16_t* Y, int l, int b, int kb, LAS float* lds, int wave_s) {
;     ...
;     const float* cwp = argf(13) + l * 1024;
;     const float cw0 = cwp[ch], cw1 = cwp[256 + ch], cw2 = cwp[512 + ch], cw3 = cwp[768 + ch], cb = argf(14)[l * 256 + ch];
;     float hs = 0.f;
;     unsigned xn[8][4], gtn[8], gtc[8];
;     const rsrc_t rs = mk_rsrc(P);
;     const int rb2 = b * SEQ * INP * 2;
;     const rsrc_t ry = mk_rsrc(Y); const int yb2 = b * SEQ * D * 2, voY = (tg * D + 512 + ch) * 2;
;     const int voX = (tg * INP + ch) * 2;
;     ...
;     LRU_LOAD(0);
.LBB0_238:
	s_or_b64 exec, exec, s[4:5]
	s_mov_b64 s[4:5], s[0:1]
	s_load_dwordx2 s[4:5], s[4:5], 0x68
	s_mov_b64 s[6:7], s[0:1]
	v_add_u32_e32 v135, s67, v135
	v_ashrrev_i32_e32 v180, 6, v135
	v_mul_lo_u32 v162, v180, s78
	s_waitcnt lgkmcnt(0)
	v_lshl_add_u64 v[160:161], s[4:5], 0, v[36:37]
	flat_load_dword v156, v[160:161]
	flat_load_dword v157, v[160:161] offset:1024
	flat_load_dword v158, v[160:161] offset:2048
	flat_load_dword v159, v[160:161] offset:3072
	s_load_dwordx2 s[4:5], s[6:7], 0x70
	v_max_i32_e32 v163, 1, v180
	v_mul_lo_u32 v163, v163, s78
	v_or_b32_e32 v163, v163, v173
	v_lshl_add_u32 v163, v163, 1, v148
	s_waitcnt lgkmcnt(0)
	v_lshl_add_u64 v[160:161], s[4:5], 0, v[36:37]
	flat_load_dword v36, v[160:161]
	v_or_b32_e32 v160, v162, v173
	v_max_i32_e32 v161, 3, v180
	v_max_i32_e32 v162, 2, v180
	v_mul_lo_u32 v161, v161, s78
	v_mul_lo_u32 v162, v162, s78
	v_or_b32_e32 v161, v161, v173
	v_or_b32_e32 v162, v162, v173
	v_lshlrev_b32_e32 v160, 1, v160
	s_or_b32 s4, s65, 0x1008
	s_or_b32 s5, s65, 0x1208
	v_lshl_add_u32 v161, v161, 1, v146
	v_lshl_add_u32 v162, v162, 1, v147
	buffer_load_ushort v174, v161, s[16:19], s5 offen
	buffer_load_ushort v175, v162, s[16:19], s5 offen
	buffer_load_ushort v176, v163, s[16:19], s5 offen
	s_or_b32 s6, s65, 0xf008
	s_or_b32 s7, s65, 0x9e08
	s_or_b32 s8, s65, 0xba08
	s_or_b32 s9, s65, 0xd608
	s_or_b32 s10, s65, 0xf208
	s_or_b32 s11, s65, 0x1d008
	buffer_load_ushort v206, v160, s[16:19], s4 offen
	buffer_load_ushort v161, v160, s[16:19], s5 offen
	buffer_load_ushort v200, v160, s[16:19], s6 offen
	buffer_load_ushort v162, v160, s[16:19], s7 offen
	buffer_load_ushort v163, v160, s[16:19], s8 offen
	buffer_load_ushort v164, v160, s[16:19], s9 offen
	buffer_load_ushort v165, v160, s[16:19], s10 offen
	buffer_load_ushort v196, v160, s[16:19], s11 offen
	s_or_b32 s4, s65, 0x17e08
	s_or_b32 s5, s65, 0x19a08
	s_or_b32 s6, s65, 0x1b608
	s_or_b32 s7, s65, 0x1d208
	s_or_b32 s8, s65, 0x2b008
	s_or_b32 s9, s65, 0x25e08
	s_or_b32 s10, s65, 0x27a08
	s_or_b32 s11, s65, 0x29608
	buffer_load_ushort v166, v160, s[16:19], s4 offen
	buffer_load_ushort v167, v160, s[16:19], s5 offen
	buffer_load_ushort v168, v160, s[16:19], s6 offen
	buffer_load_ushort v169, v160, s[16:19], s7 offen
	buffer_load_ushort v194, v160, s[16:19], s8 offen
	buffer_load_ushort v170, v160, s[16:19], s9 offen
	buffer_load_ushort v171, v160, s[16:19], s10 offen
	buffer_load_ushort v172, v160, s[16:19], s11 offen
	s_or_b32 s4, s65, 0x2b208
	s_or_b32 s5, s65, 0x39008
	s_or_b32 s6, s65, 0x33e08
	s_or_b32 s7, s65, 0x35a08
	s_or_b32 s8, s65, 0x37608
	s_or_b32 s9, s65, 0x39208
	s_or_b32 s10, s65, 0x47008
	s_or_b32 s11, s65, 0x41e08
	buffer_load_ushort v179, v160, s[16:19], s4 offen
	buffer_load_ushort v193, v160, s[16:19], s5 offen
	buffer_load_ushort v183, v160, s[16:19], s6 offen
	buffer_load_ushort v185, v160, s[16:19], s7 offen
	buffer_load_ushort v189, v160, s[16:19], s8 offen
	buffer_load_ushort v190, v160, s[16:19], s9 offen
	buffer_load_ushort v188, v160, s[16:19], s10 offen
	buffer_load_ushort v192, v160, s[16:19], s11 offen
	s_or_b32 s4, s65, 0x43a08
	s_or_b32 s5, s65, 0x45608
	s_or_b32 s6, s65, 0x47208
	s_or_b32 s7, s65, 0x55008
	s_or_b32 s8, s65, 0x4fe08
	s_or_b32 s9, s65, 0x51a08
	s_or_b32 s10, s65, 0x53608
	s_or_b32 s11, s65, 0x55208
	buffer_load_ushort v197, v160, s[16:19], s4 offen
	buffer_load_ushort v198, v160, s[16:19], s5 offen
	buffer_load_ushort v199, v160, s[16:19], s6 offen
	buffer_load_ushort v187, v160, s[16:19], s7 offen
	buffer_load_ushort v202, v160, s[16:19], s8 offen
	buffer_load_ushort v204, v160, s[16:19], s9 offen
	buffer_load_ushort v205, v160, s[16:19], s10 offen
	buffer_load_ushort v207, v160, s[16:19], s11 offen
	s_or_b32 s4, s65, 0x63008
	buffer_load_ushort v184, v160, s[16:19], s4 offen
	s_or_b32 s4, s65, 0x5de08
	s_or_b32 s5, s65, 0x5fa08
	s_or_b32 s6, s65, 0x61608
	s_or_b32 s7, s65, 0x63208
	buffer_load_ushort v209, v160, s[16:19], s4 offen
	buffer_load_ushort v210, v160, s[16:19], s5 offen
	buffer_load_ushort v211, v160, s[16:19], s6 offen
	buffer_load_ushort v213, v160, s[16:19], s7 offen
	v_cmp_lt_i32_e32 vcc, 2, v180
	v_lshlrev_b32_e32 v177, 1, v173
	v_lshlrev_b32_e32 v182, 11, v180
	s_movk_i32 s4, 0x400
	v_and_b32_e32 v178, 0x3fffffc0, v135
	s_mov_b32 s9, 0
	s_or_b32 s8, s65, 0x70000
	s_waitcnt vmcnt(0)
; __device__ __forceinline__ float softplusf_(float x) { return x > 20.f ? x : log1pf(expf(x)); }
; __device__ __forceinline__ const float* argf(int i) { return (const float*)kargs()[i]; }
; __device__ __forceinline__ void lru_job(const bf16_t* P, bf16_t* Y, int l, int b, int kb, LAS float* lds, int wave_s) {
;     ...
;     const int j = tid & 63, tg = tid >> 6, ch = kb * 64 + j;
;     typedef float f32x2_t __attribute__((ext_vector_type(2)));
;     f32x2_t wax[64];
;     { const float* wap = argf(15) + l * 16384; const float* wxp = argf(17) + l * 16384;
; #pragma unroll
;       for (int i = 0; i < 64; ++i) { wax[i].x = wap[(kb * 64 + i) * 64 + j]; wax[i].y = wxp[(kb * 64 + i) * 64 + j]; } }
;     const float ba = argf(16)[l * 256 + ch], bx = argf(18)[l * 256 + ch], spl = softplusf_(-argf(19)[l * 256 + ch]);
	v_cndmask_b32_e32 v173, 0, v174, vcc
	v_cmp_lt_i32_e32 vcc, 1, v180
	v_mov_b32_e32 v186, v206
	v_mov_b32_e32 v191, v200
	v_cndmask_b32_e32 v174, 0, v175, vcc
	v_cmp_lt_i32_e32 vcc, 0, v180
	v_mov_b32_e32 v195, v196
	s_nop 0
	v_cndmask_b32_e32 v175, 0, v176, vcc
	v_or3_b32 v176, v182, v177, s4
	v_add_u32_e32 v177, 0, v134
	v_or_b32_e32 v134, v182, v134
	v_lshl_add_u32 v178, v178, 2, v177
	v_cmp_gt_i32_e32 vcc, 64, v135
	v_lshl_add_u32 v180, v180, 8, v177
	v_add_u32_e32 v181, 0, v134
	v_add_u32_e32 v182, 0, v182
	v_mov_b32_e32 v135, 0
	v_mov_b32_e32 v201, v194
	v_mov_b32_e32 v203, v193
	v_mov_b32_e32 v208, v188
	v_mov_b32_e32 v212, v187
	v_mov_b32_e32 v214, v184
	v_mbcnt_lo_u32_b32 v101, -1, 0
	v_mbcnt_hi_u32_b32 v101, -1, v101
	v_and_b32_e32 v102, 15, v101
	v_lshrrev_b32_e32 v103, 4, v101
	s_lshr_b32 s4, s67, 6
	s_and_b32 s5, s4, 3
	s_lshr_b32 s4, s4, 2
	s_lshl_b32 s6, s5, 4
	s_lshl_b32 s7, s4, 5
	v_add_u32_e32 v104, s6, v102
	v_lshlrev_b32_e32 v105, 2, v104
	ds_bpermute_b32 v96, v105, v132
	ds_bpermute_b32 v97, v105, v133
	ds_bpermute_b32 v98, v105, v39
	v_add_u32_e32 v99, s7, v102
	v_lshlrev_b32_e32 v99, 8, v99
	v_lshl_add_u32 v99, v103, 6, v99
	v_lshl_add_u32 v100, v103, 2, s7
	v_lshlrev_b32_e32 v100, 8, v100
	v_add_u32_e32 v100, v100, v105
	v_lshlrev_b32_e32 v106, 12, v103
	v_lshl_add_u32 v106, v102, 2, v106
	s_load_dwordx2 s[10:11], s[0:1], 0x78
	s_lshl_b32 s4, s70, 14
	s_lshl_b32 s6, s5, 6
	s_add_u32 s4, s4, s6
	s_waitcnt lgkmcnt(0)
	s_add_u32 s10, s10, s4
	s_addc_u32 s11, s11, 0
	s_nop 4
	global_load_dword v0, v106, s[10:11] offset:0
	global_load_dword v1, v106, s[10:11] offset:256
	global_load_dword v2, v106, s[10:11] offset:512
	global_load_dword v3, v106, s[10:11] offset:768
	global_load_dword v4, v106, s[10:11] offset:1024
	global_load_dword v5, v106, s[10:11] offset:1280
	global_load_dword v6, v106, s[10:11] offset:1536
	global_load_dword v7, v106, s[10:11] offset:1792
	global_load_dword v8, v106, s[10:11] offset:2048
	global_load_dword v9, v106, s[10:11] offset:2304
	global_load_dword v10, v106, s[10:11] offset:2560
	global_load_dword v11, v106, s[10:11] offset:2816
	global_load_dword v12, v106, s[10:11] offset:3072
	global_load_dword v13, v106, s[10:11] offset:3328
	global_load_dword v14, v106, s[10:11] offset:3584
	global_load_dword v15, v106, s[10:11] offset:3840
	s_load_dwordx2 s[10:11], s[0:1], 0x88
	s_waitcnt lgkmcnt(0)
	s_add_u32 s10, s10, s4
	s_addc_u32 s11, s11, 0
	s_nop 4
	global_load_dword v16, v106, s[10:11] offset:0
	global_load_dword v17, v106, s[10:11] offset:256
	global_load_dword v18, v106, s[10:11] offset:512
	global_load_dword v19, v106, s[10:11] offset:768
	global_load_dword v20, v106, s[10:11] offset:1024
	global_load_dword v21, v106, s[10:11] offset:1280
	global_load_dword v22, v106, s[10:11] offset:1536
	global_load_dword v23, v106, s[10:11] offset:1792
	global_load_dword v24, v106, s[10:11] offset:2048
	global_load_dword v25, v106, s[10:11] offset:2304
	global_load_dword v26, v106, s[10:11] offset:2560
	global_load_dword v27, v106, s[10:11] offset:2816
	global_load_dword v28, v106, s[10:11] offset:3072
	global_load_dword v29, v106, s[10:11] offset:3328
	global_load_dword v30, v106, s[10:11] offset:3584
	global_load_dword v31, v106, s[10:11] offset:3840
	s_waitcnt vmcnt(0)
	s_branch .LBB0_240

; #define LAS __attribute__((address_space(3)))
; __device__ __forceinline__ void lru_job(const bf16_t* P, bf16_t* Y, int l, int b, int kb, LAS float* lds, int wave_s) {
;     ...
;         for (int tt = 0; tt < 8; ++tt) { const int t = tg * 8 + tt; f32x2_t dd = {ba, bx};
; #pragma unroll
;             for (int i4 = 0; i4 < 16; ++i4) { const f32x4 xv = *(const LAS f32x4*)(XC + t * 64 + 4 * i4);
; #pragma unroll
;                 for (int q = 0; q < 4; ++q) { const f32x2_t xb = {xv[q], xv[q]}; dd = __builtin_elementwise_fma(xb, wax[4 * i4 + q], dd); } }
.LBB0_242:
	ds_read_b128 v[40:43], v99
	ds_read_b128 v[56:59], v99 offset:4096
	ds_read_b128 v[44:47], v99 offset:16
	ds_read_b128 v[60:63], v99 offset:4112
	ds_read_b128 v[48:51], v99 offset:32
	ds_read_b128 v[64:67], v99 offset:4128
	ds_read_b128 v[52:55], v99 offset:48
	ds_read_b128 v[68:71], v99 offset:4144
	ds_read_b32 v88, v100
	ds_read_b32 v89, v100 offset:256
	ds_read_b32 v90, v100 offset:512
	ds_read_b32 v91, v100 offset:768
	ds_read_b32 v92, v100 offset:4096
	ds_read_b32 v93, v100 offset:4352
	ds_read_b32 v94, v100 offset:4608
	ds_read_b32 v95, v100 offset:4864
	v_mov_b32_e32 v72, v96
	v_mov_b32_e32 v73, v96
	v_mov_b32_e32 v74, v96
	v_mov_b32_e32 v75, v96
	v_mov_b32_e32 v76, v97
	v_mov_b32_e32 v77, v97
	v_mov_b32_e32 v78, v97
	v_mov_b32_e32 v79, v97
	v_mov_b32_e32 v80, v96
	v_mov_b32_e32 v81, v96
	v_mov_b32_e32 v82, v96
	v_mov_b32_e32 v83, v96
	v_mov_b32_e32 v84, v97
	v_mov_b32_e32 v85, v97
	v_mov_b32_e32 v86, v97
	v_mov_b32_e32 v87, v97
	s_waitcnt lgkmcnt(14)
	s_nop 1
	v_mfma_f32_16x16x4_f32 v[72:75], v40, v0, v[72:75]
	v_mfma_f32_16x16x4_f32 v[76:79], v40, v16, v[76:79]
	v_mfma_f32_16x16x4_f32 v[80:83], v56, v0, v[80:83]
	v_mfma_f32_16x16x4_f32 v[84:87], v56, v16, v[84:87]
	v_mfma_f32_16x16x4_f32 v[72:75], v41, v1, v[72:75]
	v_mfma_f32_16x16x4_f32 v[76:79], v41, v17, v[76:79]
	v_mfma_f32_16x16x4_f32 v[80:83], v57, v1, v[80:83]
	v_mfma_f32_16x16x4_f32 v[84:87], v57, v17, v[84:87]
	v_mfma_f32_16x16x4_f32 v[72:75], v42, v2, v[72:75]
	v_mfma_f32_16x16x4_f32 v[76:79], v42, v18, v[76:79]
	v_mfma_f32_16x16x4_f32 v[80:83], v58, v2, v[80:83]
	v_mfma_f32_16x16x4_f32 v[84:87], v58, v18, v[84:87]
	v_mfma_f32_16x16x4_f32 v[72:75], v43, v3, v[72:75]
	v_mfma_f32_16x16x4_f32 v[76:79], v43, v19, v[76:79]
	v_mfma_f32_16x16x4_f32 v[80:83], v59, v3, v[80:83]
	v_mfma_f32_16x16x4_f32 v[84:87], v59, v19, v[84:87]
	s_waitcnt lgkmcnt(12)
	v_mfma_f32_16x16x4_f32 v[72:75], v44, v4, v[72:75]
	v_mfma_f32_16x16x4_f32 v[76:79], v44, v20, v[76:79]
	v_mfma_f32_16x16x4_f32 v[80:83], v60, v4, v[80:83]
	v_mfma_f32_16x16x4_f32 v[84:87], v60, v20, v[84:87]
	v_mfma_f32_16x16x4_f32 v[72:75], v45, v5, v[72:75]
	v_mfma_f32_16x16x4_f32 v[76:79], v45, v21, v[76:79]
	v_mfma_f32_16x16x4_f32 v[80:83], v61, v5, v[80:83]
	v_mfma_f32_16x16x4_f32 v[84:87], v61, v21, v[84:87]
	v_mfma_f32_16x16x4_f32 v[72:75], v46, v6, v[72:75]
	v_mfma_f32_16x16x4_f32 v[76:79], v46, v22, v[76:79]
	v_mfma_f32_16x16x4_f32 v[80:83], v62, v6, v[80:83]
	v_mfma_f32_16x16x4_f32 v[84:87], v62, v22, v[84:87]
	v_mfma_f32_16x16x4_f32 v[72:75], v47, v7, v[72:75]
	v_mfma_f32_16x16x4_f32 v[76:79], v47, v23, v[76:79]
	v_mfma_f32_16x16x4_f32 v[80:83], v63, v7, v[80:83]
	v_mfma_f32_16x16x4_f32 v[84:87], v63, v23, v[84:87]
	s_waitcnt lgkmcnt(10)
	v_mfma_f32_16x16x4_f32 v[72:75], v48, v8, v[72:75]
	v_mfma_f32_16x16x4_f32 v[76:79], v48, v24, v[76:79]
	v_mfma_f32_16x16x4_f32 v[80:83], v64, v8, v[80:83]
	v_mfma_f32_16x16x4_f32 v[84:87], v64, v24, v[84:87]
	v_mfma_f32_16x16x4_f32 v[72:75], v49, v9, v[72:75]
	v_mfma_f32_16x16x4_f32 v[76:79], v49, v25, v[76:79]
	v_mfma_f32_16x16x4_f32 v[80:83], v65, v9, v[80:83]
	v_mfma_f32_16x16x4_f32 v[84:87], v65, v25, v[84:87]
	v_mfma_f32_16x16x4_f32 v[72:75], v50, v10, v[72:75]
	v_mfma_f32_16x16x4_f32 v[76:79], v50, v26, v[76:79]
	v_mfma_f32_16x16x4_f32 v[80:83], v66, v10, v[80:83]
	v_mfma_f32_16x16x4_f32 v[84:87], v66, v26, v[84:87]
	v_mfma_f32_16x16x4_f32 v[72:75], v51, v11, v[72:75]
	v_mfma_f32_16x16x4_f32 v[76:79], v51, v27, v[76:79]
	v_mfma_f32_16x16x4_f32 v[80:83], v67, v11, v[80:83]
	v_mfma_f32_16x16x4_f32 v[84:87], v67, v27, v[84:87]
	s_waitcnt lgkmcnt(8)
	v_mfma_f32_16x16x4_f32 v[72:75], v52, v12, v[72:75]
	v_mfma_f32_16x16x4_f32 v[76:79], v52, v28, v[76:79]
	v_mfma_f32_16x16x4_f32 v[80:83], v68, v12, v[80:83]
	v_mfma_f32_16x16x4_f32 v[84:87], v68, v28, v[84:87]
	v_mfma_f32_16x16x4_f32 v[72:75], v53, v13, v[72:75]
	v_mfma_f32_16x16x4_f32 v[76:79], v53, v29, v[76:79]
	v_mfma_f32_16x16x4_f32 v[80:83], v69, v13, v[80:83]
	v_mfma_f32_16x16x4_f32 v[84:87], v69, v29, v[84:87]
	v_mfma_f32_16x16x4_f32 v[72:75], v54, v14, v[72:75]
	v_mfma_f32_16x16x4_f32 v[76:79], v54, v30, v[76:79]
	v_mfma_f32_16x16x4_f32 v[80:83], v70, v14, v[80:83]
	v_mfma_f32_16x16x4_f32 v[84:87], v70, v30, v[84:87]
	v_mfma_f32_16x16x4_f32 v[72:75], v55, v15, v[72:75]
	v_mfma_f32_16x16x4_f32 v[76:79], v55, v31, v[76:79]
	v_mfma_f32_16x16x4_f32 v[80:83], v71, v15, v[80:83]
	v_mfma_f32_16x16x4_f32 v[84:87], v71, v31, v[84:87]
	s_waitcnt lgkmcnt(0)
; __device__ __forceinline__ float sigmoidf_(float x) { return __builtin_amdgcn_rcpf(1.f + __expf(-x)); }
; __device__ __forceinline__ void lru_job(const bf16_t* P, bf16_t* Y, int l, int b, int kb, LAS float* lds, int wave_s) {
;     ...
;             const float rg = sigmoidf_(dd.x), ig = sigmoidf_(dd.y);
;             const float la = -8.f * rg * spl;
;             const float av = __expf(la);
;             Aa[t * 64 + j] = av;
;             Uu[t * 64 + j] = sqrtf(fmaxf(1.f - av * av, 0.f)) * (ig * XC[t * 64 + j]); }
	s_nop 7
	s_nop 3
	v_mul_f32_e32 v101, 0xbfb8aa3b, v72
	v_exp_f32_e32 v101, v101
	v_mul_f32_e32 v102, 0xbfb8aa3b, v76
	v_exp_f32_e32 v102, v102
	s_mov_b32 s4, 0xf800000
	v_add_f32_e32 v101, 1.0, v101
	v_rcp_f32_e32 v101, v101
	v_add_f32_e32 v102, 1.0, v102
	v_rcp_f32_e32 v102, v102
	s_nop 0
	v_mul_f32_e32 v101, 0xc1000000, v101
	v_mul_f32_e32 v101, v98, v101
	v_mul_f32_e32 v101, 0x3fb8aa3b, v101
	v_exp_f32_e32 v101, v101
	v_mul_f32_e32 v102, v88, v102
	v_fma_f32 v103, -v101, v101, 1.0
	v_max_f32_e32 v103, 0, v103
	v_cmp_gt_f32_e64 s[4:5], s4, v103
	v_mul_f32_e32 v104, 0x4f800000, v103
	s_nop 0
	v_cndmask_b32_e64 v103, v103, v104, s[4:5]
	v_sqrt_f32_e32 v104, v103
	s_nop 0
	v_add_u32_e32 v105, -1, v104
	v_fma_f32 v106, -v105, v104, v103
	v_cmp_ge_f32_e64 s[6:7], 0, v106
	v_add_u32_e32 v106, 1, v104
	s_nop 0
	v_cndmask_b32_e64 v105, v104, v105, s[6:7]
	v_fma_f32 v104, -v106, v104, v103
	v_cmp_lt_f32_e64 s[6:7], 0, v104
	s_nop 1
	v_cndmask_b32_e64 v104, v105, v106, s[6:7]
	v_mul_f32_e32 v105, 0x37800000, v104
	v_cndmask_b32_e64 v104, v104, v105, s[4:5]
	v_mov_b32_e32 v105, 0x260
	v_cmp_class_f32_e64 s[4:5], v103, v105
	s_nop 1
	v_cndmask_b32_e64 v103, v104, v103, s[4:5]
	v_mul_f32_e32 v102, v102, v103
	ds_write2st64_b32 v100, v101, v102 offset0:64 offset1:128
	v_mul_f32_e32 v101, 0xbfb8aa3b, v73
	v_exp_f32_e32 v101, v101
	v_mul_f32_e32 v102, 0xbfb8aa3b, v77
	v_exp_f32_e32 v102, v102
	s_mov_b32 s4, 0xf800000
	v_add_f32_e32 v101, 1.0, v101
	v_rcp_f32_e32 v101, v101
	v_add_f32_e32 v102, 1.0, v102
	v_rcp_f32_e32 v102, v102
	s_nop 0
	v_mul_f32_e32 v101, 0xc1000000, v101
	v_mul_f32_e32 v101, v98, v101
	v_mul_f32_e32 v101, 0x3fb8aa3b, v101
	v_exp_f32_e32 v101, v101
	v_mul_f32_e32 v102, v89, v102
	v_fma_f32 v103, -v101, v101, 1.0
	v_max_f32_e32 v103, 0, v103
	v_cmp_gt_f32_e64 s[4:5], s4, v103
	v_mul_f32_e32 v104, 0x4f800000, v103
	s_nop 0
	v_cndmask_b32_e64 v103, v103, v104, s[4:5]
	v_sqrt_f32_e32 v104, v103
	s_nop 0
	v_add_u32_e32 v105, -1, v104
	v_fma_f32 v106, -v105, v104, v103
	v_cmp_ge_f32_e64 s[6:7], 0, v106
	v_add_u32_e32 v106, 1, v104
	s_nop 0
	v_cndmask_b32_e64 v105, v104, v105, s[6:7]
	v_fma_f32 v104, -v106, v104, v103
	v_cmp_lt_f32_e64 s[6:7], 0, v104
	s_nop 1
	v_cndmask_b32_e64 v104, v105, v106, s[6:7]
	v_mul_f32_e32 v105, 0x37800000, v104
	v_cndmask_b32_e64 v104, v104, v105, s[4:5]
	v_mov_b32_e32 v105, 0x260
	v_cmp_class_f32_e64 s[4:5], v103, v105
	s_nop 1
	v_cndmask_b32_e64 v103, v104, v103, s[4:5]
	v_mul_f32_e32 v102, v102, v103
	ds_write2st64_b32 v100, v101, v102 offset0:65 offset1:129
	v_mul_f32_e32 v101, 0xbfb8aa3b, v74
	v_exp_f32_e32 v101, v101
	v_mul_f32_e32 v102, 0xbfb8aa3b, v78
	v_exp_f32_e32 v102, v102
	s_mov_b32 s4, 0xf800000
	v_add_f32_e32 v101, 1.0, v101
	v_rcp_f32_e32 v101, v101
	v_add_f32_e32 v102, 1.0, v102
	v_rcp_f32_e32 v102, v102
	s_nop 0
	v_mul_f32_e32 v101, 0xc1000000, v101
	v_mul_f32_e32 v101, v98, v101
	v_mul_f32_e32 v101, 0x3fb8aa3b, v101
	v_exp_f32_e32 v101, v101
	v_mul_f32_e32 v102, v90, v102
	v_fma_f32 v103, -v101, v101, 1.0
	v_max_f32_e32 v103, 0, v103
	v_cmp_gt_f32_e64 s[4:5], s4, v103
	v_mul_f32_e32 v104, 0x4f800000, v103
	s_nop 0
	v_cndmask_b32_e64 v103, v103, v104, s[4:5]
	v_sqrt_f32_e32 v104, v103
	s_nop 0
	v_add_u32_e32 v105, -1, v104
	v_fma_f32 v106, -v105, v104, v103
	v_cmp_ge_f32_e64 s[6:7], 0, v106
	v_add_u32_e32 v106, 1, v104
	s_nop 0
	v_cndmask_b32_e64 v105, v104, v105, s[6:7]
	v_fma_f32 v104, -v106, v104, v103
	v_cmp_lt_f32_e64 s[6:7], 0, v104
	s_nop 1
	v_cndmask_b32_e64 v104, v105, v106, s[6:7]
	v_mul_f32_e32 v105, 0x37800000, v104
	v_cndmask_b32_e64 v104, v104, v105, s[4:5]
	v_mov_b32_e32 v105, 0x260
	v_cmp_class_f32_e64 s[4:5], v103, v105
	s_nop 1
	v_cndmask_b32_e64 v103, v104, v103, s[4:5]
	v_mul_f32_e32 v102, v102, v103
	ds_write2st64_b32 v100, v101, v102 offset0:66 offset1:130
	v_mul_f32_e32 v101, 0xbfb8aa3b, v75
	v_exp_f32_e32 v101, v101
	v_mul_f32_e32 v102, 0xbfb8aa3b, v79
	v_exp_f32_e32 v102, v102
	s_mov_b32 s4, 0xf800000
	v_add_f32_e32 v101, 1.0, v101
	v_rcp_f32_e32 v101, v101
	v_add_f32_e32 v102, 1.0, v102
	v_rcp_f32_e32 v102, v102
	s_nop 0
	v_mul_f32_e32 v101, 0xc1000000, v101
	v_mul_f32_e32 v101, v98, v101
	v_mul_f32_e32 v101, 0x3fb8aa3b, v101
	v_exp_f32_e32 v101, v101
	v_mul_f32_e32 v102, v91, v102
	v_fma_f32 v103, -v101, v101, 1.0
	v_max_f32_e32 v103, 0, v103
	v_cmp_gt_f32_e64 s[4:5], s4, v103
	v_mul_f32_e32 v104, 0x4f800000, v103
	s_nop 0
	v_cndmask_b32_e64 v103, v103, v104, s[4:5]
	v_sqrt_f32_e32 v104, v103
	s_nop 0
	v_add_u32_e32 v105, -1, v104
	v_fma_f32 v106, -v105, v104, v103
	v_cmp_ge_f32_e64 s[6:7], 0, v106
	v_add_u32_e32 v106, 1, v104
	s_nop 0
	v_cndmask_b32_e64 v105, v104, v105, s[6:7]
	v_fma_f32 v104, -v106, v104, v103
	v_cmp_lt_f32_e64 s[6:7], 0, v104
	s_nop 1
	v_cndmask_b32_e64 v104, v105, v106, s[6:7]
	v_mul_f32_e32 v105, 0x37800000, v104
	v_cndmask_b32_e64 v104, v104, v105, s[4:5]
	v_mov_b32_e32 v105, 0x260
	v_cmp_class_f32_e64 s[4:5], v103, v105
	s_nop 1
	v_cndmask_b32_e64 v103, v104, v103, s[4:5]
	v_mul_f32_e32 v102, v102, v103
	ds_write2st64_b32 v100, v101, v102 offset0:67 offset1:131
	v_mul_f32_e32 v101, 0xbfb8aa3b, v80
	v_exp_f32_e32 v101, v101
	v_mul_f32_e32 v102, 0xbfb8aa3b, v84
	v_exp_f32_e32 v102, v102
	s_mov_b32 s4, 0xf800000
	v_add_f32_e32 v101, 1.0, v101
	v_rcp_f32_e32 v101, v101
	v_add_f32_e32 v102, 1.0, v102
	v_rcp_f32_e32 v102, v102
	s_nop 0
	v_mul_f32_e32 v101, 0xc1000000, v101
	v_mul_f32_e32 v101, v98, v101
	v_mul_f32_e32 v101, 0x3fb8aa3b, v101
	v_exp_f32_e32 v101, v101
	v_mul_f32_e32 v102, v92, v102
	v_fma_f32 v103, -v101, v101, 1.0
	v_max_f32_e32 v103, 0, v103
	v_cmp_gt_f32_e64 s[4:5], s4, v103
	v_mul_f32_e32 v104, 0x4f800000, v103
	s_nop 0
; __device__ __forceinline__ float sigmoidf_(float x) { return __builtin_amdgcn_rcpf(1.f + __expf(-x)); }
; __device__ __forceinline__ void lru_job(const bf16_t* P, bf16_t* Y, int l, int b, int kb, LAS float* lds, int wave_s) {
;     ...
;             const float rg = sigmoidf_(dd.x), ig = sigmoidf_(dd.y);
;             const float la = -8.f * rg * spl;
;             const float av = __expf(la);
;             Aa[t * 64 + j] = av;
;             Uu[t * 64 + j] = sqrtf(fmaxf(1.f - av * av, 0.f)) * (ig * XC[t * 64 + j]); }
;         __syncthreads();
	v_cndmask_b32_e64 v103, v103, v104, s[4:5]
	v_sqrt_f32_e32 v104, v103
	s_nop 0
	v_add_u32_e32 v105, -1, v104
	v_fma_f32 v106, -v105, v104, v103
	v_cmp_ge_f32_e64 s[6:7], 0, v106
	v_add_u32_e32 v106, 1, v104
	s_nop 0
	v_cndmask_b32_e64 v105, v104, v105, s[6:7]
	v_fma_f32 v104, -v106, v104, v103
	v_cmp_lt_f32_e64 s[6:7], 0, v104
	s_nop 1
	v_cndmask_b32_e64 v104, v105, v106, s[6:7]
	v_mul_f32_e32 v105, 0x37800000, v104
	v_cndmask_b32_e64 v104, v104, v105, s[4:5]
	v_mov_b32_e32 v105, 0x260
	v_cmp_class_f32_e64 s[4:5], v103, v105
	s_nop 1
	v_cndmask_b32_e64 v103, v104, v103, s[4:5]
	v_mul_f32_e32 v102, v102, v103
	ds_write2st64_b32 v100, v101, v102 offset0:80 offset1:144
	v_mul_f32_e32 v101, 0xbfb8aa3b, v81
	v_exp_f32_e32 v101, v101
	v_mul_f32_e32 v102, 0xbfb8aa3b, v85
	v_exp_f32_e32 v102, v102
	s_mov_b32 s4, 0xf800000
	v_add_f32_e32 v101, 1.0, v101
	v_rcp_f32_e32 v101, v101
	v_add_f32_e32 v102, 1.0, v102
	v_rcp_f32_e32 v102, v102
	s_nop 0
	v_mul_f32_e32 v101, 0xc1000000, v101
	v_mul_f32_e32 v101, v98, v101
	v_mul_f32_e32 v101, 0x3fb8aa3b, v101
	v_exp_f32_e32 v101, v101
	v_mul_f32_e32 v102, v93, v102
	v_fma_f32 v103, -v101, v101, 1.0
	v_max_f32_e32 v103, 0, v103
	v_cmp_gt_f32_e64 s[4:5], s4, v103
	v_mul_f32_e32 v104, 0x4f800000, v103
	s_nop 0
	v_cndmask_b32_e64 v103, v103, v104, s[4:5]
	v_sqrt_f32_e32 v104, v103
	s_nop 0
	v_add_u32_e32 v105, -1, v104
	v_fma_f32 v106, -v105, v104, v103
	v_cmp_ge_f32_e64 s[6:7], 0, v106
	v_add_u32_e32 v106, 1, v104
	s_nop 0
	v_cndmask_b32_e64 v105, v104, v105, s[6:7]
	v_fma_f32 v104, -v106, v104, v103
	v_cmp_lt_f32_e64 s[6:7], 0, v104
	s_nop 1
	v_cndmask_b32_e64 v104, v105, v106, s[6:7]
	v_mul_f32_e32 v105, 0x37800000, v104
	v_cndmask_b32_e64 v104, v104, v105, s[4:5]
	v_mov_b32_e32 v105, 0x260
	v_cmp_class_f32_e64 s[4:5], v103, v105
	s_nop 1
	v_cndmask_b32_e64 v103, v104, v103, s[4:5]
	v_mul_f32_e32 v102, v102, v103
	ds_write2st64_b32 v100, v101, v102 offset0:81 offset1:145
	v_mul_f32_e32 v101, 0xbfb8aa3b, v82
	v_exp_f32_e32 v101, v101
	v_mul_f32_e32 v102, 0xbfb8aa3b, v86
	v_exp_f32_e32 v102, v102
	s_mov_b32 s4, 0xf800000
	v_add_f32_e32 v101, 1.0, v101
	v_rcp_f32_e32 v101, v101
	v_add_f32_e32 v102, 1.0, v102
	v_rcp_f32_e32 v102, v102
	s_nop 0
	v_mul_f32_e32 v101, 0xc1000000, v101
	v_mul_f32_e32 v101, v98, v101
	v_mul_f32_e32 v101, 0x3fb8aa3b, v101
	v_exp_f32_e32 v101, v101
	v_mul_f32_e32 v102, v94, v102
	v_fma_f32 v103, -v101, v101, 1.0
	v_max_f32_e32 v103, 0, v103
	v_cmp_gt_f32_e64 s[4:5], s4, v103
	v_mul_f32_e32 v104, 0x4f800000, v103
	s_nop 0
	v_cndmask_b32_e64 v103, v103, v104, s[4:5]
	v_sqrt_f32_e32 v104, v103
	s_nop 0
	v_add_u32_e32 v105, -1, v104
	v_fma_f32 v106, -v105, v104, v103
	v_cmp_ge_f32_e64 s[6:7], 0, v106
	v_add_u32_e32 v106, 1, v104
	s_nop 0
	v_cndmask_b32_e64 v105, v104, v105, s[6:7]
	v_fma_f32 v104, -v106, v104, v103
	v_cmp_lt_f32_e64 s[6:7], 0, v104
	s_nop 1
	v_cndmask_b32_e64 v104, v105, v106, s[6:7]
	v_mul_f32_e32 v105, 0x37800000, v104
	v_cndmask_b32_e64 v104, v104, v105, s[4:5]
	v_mov_b32_e32 v105, 0x260
	v_cmp_class_f32_e64 s[4:5], v103, v105
	s_nop 1
	v_cndmask_b32_e64 v103, v104, v103, s[4:5]
	v_mul_f32_e32 v102, v102, v103
	ds_write2st64_b32 v100, v101, v102 offset0:82 offset1:146
	v_mul_f32_e32 v101, 0xbfb8aa3b, v83
	v_exp_f32_e32 v101, v101
	v_mul_f32_e32 v102, 0xbfb8aa3b, v87
	v_exp_f32_e32 v102, v102
	s_mov_b32 s4, 0xf800000
	v_add_f32_e32 v101, 1.0, v101
	v_rcp_f32_e32 v101, v101
	v_add_f32_e32 v102, 1.0, v102
	v_rcp_f32_e32 v102, v102
	s_nop 0
	v_mul_f32_e32 v101, 0xc1000000, v101
	v_mul_f32_e32 v101, v98, v101
	v_mul_f32_e32 v101, 0x3fb8aa3b, v101
	v_exp_f32_e32 v101, v101
	v_mul_f32_e32 v102, v95, v102
	v_fma_f32 v103, -v101, v101, 1.0
	v_max_f32_e32 v103, 0, v103
	v_cmp_gt_f32_e64 s[4:5], s4, v103
	v_mul_f32_e32 v104, 0x4f800000, v103
	s_nop 0
	v_cndmask_b32_e64 v103, v103, v104, s[4:5]
	v_sqrt_f32_e32 v104, v103
	s_nop 0
	v_add_u32_e32 v105, -1, v104
	v_fma_f32 v106, -v105, v104, v103
	v_cmp_ge_f32_e64 s[6:7], 0, v106
	v_add_u32_e32 v106, 1, v104
	s_nop 0
	v_cndmask_b32_e64 v105, v104, v105, s[6:7]
	v_fma_f32 v104, -v106, v104, v103
	v_cmp_lt_f32_e64 s[6:7], 0, v104
	s_nop 1
	v_cndmask_b32_e64 v104, v105, v106, s[6:7]
	v_mul_f32_e32 v105, 0x37800000, v104
	v_cndmask_b32_e64 v104, v104, v105, s[4:5]
	v_mov_b32_e32 v105, 0x260
	v_cmp_class_f32_e64 s[4:5], v103, v105
	s_nop 1
	v_cndmask_b32_e64 v103, v104, v103, s[4:5]
	v_mul_f32_e32 v102, v102, v103
	ds_write2st64_b32 v100, v101, v102 offset0:83 offset1:147
	s_waitcnt lgkmcnt(0)
	s_barrier
	s_and_saveexec_b64 s[4:5], vcc
	s_cbranch_execz .LBB0_239
; __device__ __forceinline__ void lru_job(const bf16_t* P, bf16_t* Y, int l, int b, int kb, LAS float* lds, int wave_s) {
;     ...
;         if (tid < 64) {
;             for (int tb = 0; tb < TC; tb += 8) { float av[8], uv[8];
; #pragma unroll
;                 for (int k = 0; k < 8; ++k) { av[k] = Aa[(tb + k) * 64 + j]; uv[k] = Uu[(tb + k) * 64 + j]; }
; #pragma unroll
;                 for (int k = 0; k < 8; ++k) { hs = av[k] * hs + uv[k]; Hh[(tb + k) * 64 + j] = hs; } }
;         }
	ds_read2st64_b32 v[216:217], v177 offset0:128 offset1:129
	ds_read2st64_b32 v[218:219], v177 offset0:64 offset1:65
	ds_read2st64_b32 v[220:221], v177 offset0:66 offset1:67
	ds_read2st64_b32 v[222:223], v177 offset0:68 offset1:69
	ds_read2st64_b32 v[224:225], v177 offset0:70 offset1:71
	ds_read2st64_b32 v[226:227], v177 offset0:130 offset1:131
	ds_read2st64_b32 v[228:229], v177 offset0:132 offset1:133
	ds_read2st64_b32 v[230:231], v177 offset0:134 offset1:135
	s_waitcnt lgkmcnt(6)
	v_fma_f32 v134, v135, v218, v216
	v_fmac_f32_e32 v217, v134, v219
	ds_write2st64_b32 v177, v134, v217 offset0:192 offset1:193
	s_waitcnt lgkmcnt(3)
	v_fma_f32 v134, v217, v220, v226
	v_fmac_f32_e32 v227, v134, v221
	ds_write2st64_b32 v177, v134, v227 offset0:194 offset1:195
	s_waitcnt lgkmcnt(3)
	v_fma_f32 v134, v227, v222, v228
	v_fmac_f32_e32 v229, v134, v223
	ds_write2st64_b32 v177, v134, v229 offset0:196 offset1:197
	s_waitcnt lgkmcnt(3)
	v_fma_f32 v134, v229, v224, v230
	v_fmac_f32_e32 v231, v134, v225
	ds_write2st64_b32 v177, v134, v231 offset0:198 offset1:199
	ds_read2st64_b32 v[134:135], v177 offset0:136 offset1:137
	ds_read2st64_b32 v[216:217], v177 offset0:72 offset1:73
	ds_read2st64_b32 v[218:219], v177 offset0:74 offset1:75
	ds_read2st64_b32 v[220:221], v177 offset0:76 offset1:77
	ds_read2st64_b32 v[222:223], v177 offset0:78 offset1:79
	ds_read2st64_b32 v[224:225], v177 offset0:138 offset1:139
	ds_read2st64_b32 v[226:227], v177 offset0:140 offset1:141
	ds_read2st64_b32 v[228:229], v177 offset0:142 offset1:143
	s_waitcnt lgkmcnt(6)
	v_fma_f32 v134, v231, v216, v134
	v_fmac_f32_e32 v135, v134, v217
	ds_write2st64_b32 v177, v134, v135 offset0:200 offset1:201
	s_waitcnt lgkmcnt(3)
	v_fma_f32 v134, v135, v218, v224
	v_fmac_f32_e32 v225, v134, v219
	ds_write2st64_b32 v177, v134, v225 offset0:202 offset1:203
	s_waitcnt lgkmcnt(3)
	v_fma_f32 v134, v225, v220, v226
	v_fmac_f32_e32 v227, v134, v221
	ds_write2st64_b32 v177, v134, v227 offset0:204 offset1:205
	s_waitcnt lgkmcnt(3)
	v_fma_f32 v134, v227, v222, v228
	v_fmac_f32_e32 v229, v134, v223
	ds_write2st64_b32 v177, v134, v229 offset0:206 offset1:207
	ds_read2st64_b32 v[134:135], v177 offset0:144 offset1:145
	ds_read2st64_b32 v[216:217], v177 offset0:80 offset1:81
	ds_read2st64_b32 v[218:219], v177 offset0:82 offset1:83
	ds_read2st64_b32 v[220:221], v177 offset0:84 offset1:85
	ds_read2st64_b32 v[222:223], v177 offset0:86 offset1:87
	ds_read2st64_b32 v[224:225], v177 offset0:146 offset1:147
	ds_read2st64_b32 v[226:227], v177 offset0:148 offset1:149
	ds_read2st64_b32 v[230:231], v177 offset0:150 offset1:151
	s_waitcnt lgkmcnt(6)
	v_fma_f32 v134, v229, v216, v134
	v_fmac_f32_e32 v135, v134, v217
	ds_write2st64_b32 v177, v134, v135 offset0:208 offset1:209
	s_waitcnt lgkmcnt(3)
	v_fma_f32 v134, v135, v218, v224
	v_fmac_f32_e32 v225, v134, v219
	ds_write2st64_b32 v177, v134, v225 offset0:210 offset1:211
	s_waitcnt lgkmcnt(3)
	v_fma_f32 v134, v225, v220, v226
	v_fmac_f32_e32 v227, v134, v221
	ds_write2st64_b32 v177, v134, v227 offset0:212 offset1:213
	s_waitcnt lgkmcnt(3)
	v_fma_f32 v134, v227, v222, v230
	v_fmac_f32_e32 v231, v134, v223
	ds_write2st64_b32 v177, v134, v231 offset0:214 offset1:215
	ds_read2st64_b32 v[134:135], v177 offset0:152 offset1:153
	ds_read2st64_b32 v[216:217], v177 offset0:88 offset1:89
	ds_read2st64_b32 v[218:219], v177 offset0:90 offset1:91
	ds_read2st64_b32 v[220:221], v177 offset0:92 offset1:93
	ds_read2st64_b32 v[222:223], v177 offset0:94 offset1:95
	ds_read2st64_b32 v[224:225], v177 offset0:154 offset1:155
	ds_read2st64_b32 v[226:227], v177 offset0:156 offset1:157
	ds_read2st64_b32 v[228:229], v177 offset0:158 offset1:159
	s_waitcnt lgkmcnt(6)
	v_fma_f32 v134, v231, v216, v134
	v_fmac_f32_e32 v135, v134, v217
	ds_write2st64_b32 v177, v134, v135 offset0:216 offset1:217
	s_waitcnt lgkmcnt(3)
	v_fma_f32 v134, v135, v218, v224
	v_fmac_f32_e32 v225, v134, v219
	ds_write2st64_b32 v177, v134, v225 offset0:218 offset1:219
	s_waitcnt lgkmcnt(3)
	v_fma_f32 v134, v225, v220, v226
	v_fmac_f32_e32 v227, v134, v221
	ds_write2st64_b32 v177, v134, v227 offset0:220 offset1:221
	s_waitcnt lgkmcnt(3)
; __device__ __forceinline__ void lru_job(const bf16_t* P, bf16_t* Y, int l, int b, int kb, LAS float* lds, int wave_s) {
;     ...
;         if (tid < 64) {
;             for (int tb = 0; tb < TC; tb += 8) { float av[8], uv[8];
; #pragma unroll
;                 for (int k = 0; k < 8; ++k) { av[k] = Aa[(tb + k) * 64 + j]; uv[k] = Uu[(tb + k) * 64 + j]; }
; #pragma unroll
;                 for (int k = 0; k < 8; ++k) { hs = av[k] * hs + uv[k]; Hh[(tb + k) * 64 + j] = hs; } }
;         }
	v_fma_f32 v134, v227, v222, v228
	v_fmac_f32_e32 v229, v134, v223
	ds_write2st64_b32 v177, v134, v229 offset0:222 offset1:223
	ds_read2st64_b32 v[134:135], v177 offset0:160 offset1:161
	ds_read2st64_b32 v[216:217], v177 offset0:96 offset1:97
	ds_read2st64_b32 v[218:219], v177 offset0:98 offset1:99
	ds_read2st64_b32 v[220:221], v177 offset0:100 offset1:101
	ds_read2st64_b32 v[222:223], v177 offset0:102 offset1:103
	ds_read2st64_b32 v[224:225], v177 offset0:162 offset1:163
	ds_read2st64_b32 v[226:227], v177 offset0:164 offset1:165
	ds_read2st64_b32 v[230:231], v177 offset0:166 offset1:167
	s_waitcnt lgkmcnt(6)
	v_fma_f32 v134, v229, v216, v134
	v_fmac_f32_e32 v135, v134, v217
	ds_write2st64_b32 v177, v134, v135 offset0:224 offset1:225
	s_waitcnt lgkmcnt(3)
	v_fma_f32 v134, v135, v218, v224
	v_fmac_f32_e32 v225, v134, v219
	ds_write2st64_b32 v177, v134, v225 offset0:226 offset1:227
	s_waitcnt lgkmcnt(3)
	v_fma_f32 v134, v225, v220, v226
	v_fmac_f32_e32 v227, v134, v221
	ds_write2st64_b32 v177, v134, v227 offset0:228 offset1:229
	s_waitcnt lgkmcnt(3)
	v_fma_f32 v134, v227, v222, v230
	v_fmac_f32_e32 v231, v134, v223
	ds_write2st64_b32 v177, v134, v231 offset0:230 offset1:231
	ds_read2st64_b32 v[134:135], v177 offset0:168 offset1:169
	ds_read2st64_b32 v[216:217], v177 offset0:104 offset1:105
	ds_read2st64_b32 v[218:219], v177 offset0:106 offset1:107
	ds_read2st64_b32 v[220:221], v177 offset0:108 offset1:109
	ds_read2st64_b32 v[222:223], v177 offset0:110 offset1:111
	ds_read2st64_b32 v[224:225], v177 offset0:170 offset1:171
	ds_read2st64_b32 v[226:227], v177 offset0:172 offset1:173
	ds_read2st64_b32 v[228:229], v177 offset0:174 offset1:175
	s_waitcnt lgkmcnt(6)
	v_fma_f32 v134, v231, v216, v134
	v_fmac_f32_e32 v135, v134, v217
	ds_write2st64_b32 v177, v134, v135 offset0:232 offset1:233
	s_waitcnt lgkmcnt(3)
	v_fma_f32 v134, v135, v218, v224
	v_fmac_f32_e32 v225, v134, v219
	ds_write2st64_b32 v177, v134, v225 offset0:234 offset1:235
	s_waitcnt lgkmcnt(3)
	v_fma_f32 v134, v225, v220, v226
	v_fmac_f32_e32 v227, v134, v221
	ds_write2st64_b32 v177, v134, v227 offset0:236 offset1:237
	s_waitcnt lgkmcnt(3)
	v_fma_f32 v134, v227, v222, v228
	v_fmac_f32_e32 v229, v134, v223
	ds_write2st64_b32 v177, v134, v229 offset0:238 offset1:239
	ds_read2st64_b32 v[134:135], v177 offset0:176 offset1:177
	ds_read2st64_b32 v[216:217], v177 offset0:112 offset1:113
	ds_read2st64_b32 v[218:219], v177 offset0:114 offset1:115
	ds_read2st64_b32 v[220:221], v177 offset0:116 offset1:117
	ds_read2st64_b32 v[222:223], v177 offset0:118 offset1:119
	ds_read2st64_b32 v[224:225], v177 offset0:178 offset1:179
	ds_read2st64_b32 v[226:227], v177 offset0:180 offset1:181
	ds_read2st64_b32 v[230:231], v177 offset0:182 offset1:183
	s_waitcnt lgkmcnt(6)
	v_fma_f32 v134, v229, v216, v134
	v_fmac_f32_e32 v135, v134, v217
	ds_write2st64_b32 v177, v134, v135 offset0:240 offset1:241
	s_waitcnt lgkmcnt(3)
	v_fma_f32 v134, v135, v218, v224
	v_fmac_f32_e32 v225, v134, v219
	ds_write2st64_b32 v177, v134, v225 offset0:242 offset1:243
	s_waitcnt lgkmcnt(3)
	v_fma_f32 v134, v225, v220, v226
	v_fmac_f32_e32 v227, v134, v221
	ds_write2st64_b32 v177, v134, v227 offset0:244 offset1:245
	s_waitcnt lgkmcnt(3)
	v_fma_f32 v134, v227, v222, v230
	v_fmac_f32_e32 v231, v134, v223
	ds_write2st64_b32 v177, v134, v231 offset0:246 offset1:247
	ds_read2st64_b32 v[216:217], v177 offset0:184 offset1:185
	ds_read2st64_b32 v[218:219], v177 offset0:120 offset1:121
	ds_read2st64_b32 v[220:221], v177 offset0:122 offset1:123
	ds_read2st64_b32 v[222:223], v177 offset0:124 offset1:125
	ds_read2st64_b32 v[224:225], v177 offset0:126 offset1:127
	ds_read2st64_b32 v[226:227], v177 offset0:186 offset1:187
	ds_read2st64_b32 v[228:229], v177 offset0:188 offset1:189
	ds_read2st64_b32 v[134:135], v177 offset0:190 offset1:191
	s_waitcnt lgkmcnt(6)
	v_fma_f32 v215, v231, v218, v216
	v_fmac_f32_e32 v217, v215, v219
	ds_write2st64_b32 v177, v215, v217 offset0:248 offset1:249
	s_waitcnt lgkmcnt(3)
	v_fma_f32 v215, v217, v220, v226
	v_fmac_f32_e32 v227, v215, v221
	ds_write2st64_b32 v177, v215, v227 offset0:250 offset1:251
	s_waitcnt lgkmcnt(3)
	v_fma_f32 v215, v227, v222, v228
	v_fmac_f32_e32 v229, v215, v223
	s_waitcnt lgkmcnt(2)
	v_fma_f32 v134, v229, v224, v134
	v_fmac_f32_e32 v135, v134, v225
	ds_write2st64_b32 v177, v215, v229 offset0:252 offset1:253
	ds_write2st64_b32 v177, v134, v135 offset0:254 offset1:255
	s_branch .LBB0_239

; __device__ __forceinline__ const float* argf(int i) { return (const float*)kargs()[i]; }
; __device__ __forceinline__ rsrc_t mk_rsrc(const void* p) { return __builtin_amdgcn_make_buffer_rsrc((void*)p, 0, 0x7fffffff, 0x00020000); }
; __device__ __forceinline__ void lru_job(const bf16_t* P, bf16_t* Y, int l, int b, int kb, LAS float* lds, int wave_s) {
;     ...
;     const float* cwp = argf(13) + l * 1024;
;     const float cw0 = cwp[ch], cw1 = cwp[256 + ch], cw2 = cwp[512 + ch], cw3 = cwp[768 + ch], cb = argf(14)[l * 256 + ch];
;     float hs = 0.f;
;     unsigned xn[8][4], gtn[8], gtc[8];
;     const rsrc_t rs = mk_rsrc(P);
;     const int rb2 = b * SEQ * INP * 2;
;     const rsrc_t ry = mk_rsrc(Y); const int yb2 = b * SEQ * D * 2, voY = (tg * D + 512 + ch) * 2;
;     const int voX = (tg * INP + ch) * 2;
;     ...
;     LRU_LOAD(0);
.LBB0_951:
	s_or_b64 exec, exec, s[4:5]
	s_mov_b64 s[4:5], s[0:1]
	s_load_dwordx2 s[4:5], s[4:5], 0x68
	s_mov_b64 s[6:7], 0x1000
	v_add_u32_e32 v135, s67, v135
	v_ashrrev_i32_e32 v179, 6, v135
	v_max_i32_e32 v164, 1, v179
	s_waitcnt lgkmcnt(0)
	v_lshl_add_u64 v[158:159], s[4:5], 0, v[36:37]
	v_lshl_add_u64 v[160:161], v[158:159], 0, s[6:7]
	v_add_co_u32_e32 v158, vcc, s63, v158
	s_mov_b64 s[4:5], s[0:1]
	s_nop 0
	v_addc_co_u32_e32 v159, vcc, 0, v159, vcc
	flat_load_dword v157, v[160:161] offset:1024
	s_nop 0
	flat_load_dword v158, v[158:159]
	s_nop 0
	flat_load_dword v159, v[160:161] offset:2048
	s_nop 0
	flat_load_dword v160, v[160:161] offset:3072
	s_load_dwordx2 s[4:5], s[4:5], 0x70
	v_mul_lo_u32 v161, v179, s78
	v_mul_lo_u32 v164, v164, s78
	v_or_b32_e32 v161, v161, v174
	v_or_b32_e32 v164, v164, v174
	s_waitcnt lgkmcnt(0)
	v_lshl_add_u64 v[162:163], s[4:5], 0, v[36:37]
	flat_load_dword v36, v[162:163] offset:1024
	v_max_i32_e32 v162, 3, v179
	v_max_i32_e32 v163, 2, v179
	v_mul_lo_u32 v162, v162, s78
	v_mul_lo_u32 v163, v163, s78
	v_or_b32_e32 v162, v162, v174
	v_or_b32_e32 v163, v163, v174
	v_lshlrev_b32_e32 v161, 1, v161
	s_or_b32 s4, s12, 0x1008
	s_or_b32 s5, s12, 0x1208
	v_lshl_add_u32 v162, v162, 1, v147
	v_lshl_add_u32 v163, v163, 1, v148
	v_lshl_add_u32 v164, v164, 1, v149
	buffer_load_ushort v175, v162, s[16:19], s5 offen
	buffer_load_ushort v176, v163, s[16:19], s5 offen
	buffer_load_ushort v177, v164, s[16:19], s5 offen
	s_or_b32 s6, s12, 0xf008
	s_or_b32 s7, s12, 0x9e08
	s_or_b32 s8, s12, 0xba08
	s_or_b32 s9, s12, 0xd608
	s_or_b32 s10, s12, 0xf208
	s_or_b32 s11, s12, 0x1d008
	buffer_load_ushort v207, v161, s[16:19], s4 offen
	buffer_load_ushort v162, v161, s[16:19], s5 offen
	buffer_load_ushort v202, v161, s[16:19], s6 offen
	buffer_load_ushort v163, v161, s[16:19], s7 offen
	buffer_load_ushort v164, v161, s[16:19], s8 offen
	buffer_load_ushort v165, v161, s[16:19], s9 offen
	buffer_load_ushort v166, v161, s[16:19], s10 offen
	buffer_load_ushort v197, v161, s[16:19], s11 offen
	s_or_b32 s4, s12, 0x17e08
	s_or_b32 s5, s12, 0x19a08
	s_or_b32 s6, s12, 0x1b608
	s_or_b32 s7, s12, 0x1d208
	s_or_b32 s8, s12, 0x2b008
	s_or_b32 s9, s12, 0x25e08
	s_or_b32 s10, s12, 0x27a08
	s_or_b32 s11, s12, 0x29608
	buffer_load_ushort v167, v161, s[16:19], s4 offen
	buffer_load_ushort v168, v161, s[16:19], s5 offen
	buffer_load_ushort v169, v161, s[16:19], s6 offen
	buffer_load_ushort v170, v161, s[16:19], s7 offen
	buffer_load_ushort v196, v161, s[16:19], s8 offen
	buffer_load_ushort v171, v161, s[16:19], s9 offen
	buffer_load_ushort v172, v161, s[16:19], s10 offen
	buffer_load_ushort v173, v161, s[16:19], s11 offen
	s_or_b32 s4, s12, 0x2b208
	s_or_b32 s5, s12, 0x39008
	s_or_b32 s6, s12, 0x33e08
	s_or_b32 s7, s12, 0x35a08
	s_or_b32 s8, s12, 0x37608
	s_or_b32 s9, s12, 0x39208
	s_or_b32 s10, s12, 0x47008
	s_or_b32 s11, s12, 0x41e08
	buffer_load_ushort v183, v161, s[16:19], s4 offen
	buffer_load_ushort v195, v161, s[16:19], s5 offen
	buffer_load_ushort v185, v161, s[16:19], s6 offen
	buffer_load_ushort v187, v161, s[16:19], s7 offen
	buffer_load_ushort v191, v161, s[16:19], s8 offen
	buffer_load_ushort v192, v161, s[16:19], s9 offen
	buffer_load_ushort v190, v161, s[16:19], s10 offen
	buffer_load_ushort v194, v161, s[16:19], s11 offen
	s_or_b32 s4, s12, 0x43a08
	s_or_b32 s5, s12, 0x45608
	s_or_b32 s6, s12, 0x47208
	s_or_b32 s7, s12, 0x55008
	s_or_b32 s8, s12, 0x4fe08
	s_or_b32 s9, s12, 0x51a08
	s_or_b32 s10, s12, 0x53608
	s_or_b32 s11, s12, 0x55208
	buffer_load_ushort v198, v161, s[16:19], s4 offen
	buffer_load_ushort v199, v161, s[16:19], s5 offen
	buffer_load_ushort v201, v161, s[16:19], s6 offen
	buffer_load_ushort v189, v161, s[16:19], s7 offen
	buffer_load_ushort v204, v161, s[16:19], s8 offen
	buffer_load_ushort v205, v161, s[16:19], s9 offen
	buffer_load_ushort v206, v161, s[16:19], s10 offen
	buffer_load_ushort v209, v161, s[16:19], s11 offen
	s_or_b32 s4, s12, 0x63008
	buffer_load_ushort v186, v161, s[16:19], s4 offen
	s_or_b32 s4, s12, 0x5de08
	s_or_b32 s5, s12, 0x5fa08
	s_or_b32 s6, s12, 0x61608
	s_or_b32 s7, s12, 0x63208
	buffer_load_ushort v211, v161, s[16:19], s4 offen
	buffer_load_ushort v212, v161, s[16:19], s5 offen
	buffer_load_ushort v213, v161, s[16:19], s6 offen
	buffer_load_ushort v215, v161, s[16:19], s7 offen
	v_cmp_lt_i32_e32 vcc, 2, v179
	v_lshlrev_b32_e32 v180, 1, v174
	v_lshlrev_b32_e32 v181, 11, v179
	s_movk_i32 s4, 0x400
	s_mov_b32 s9, 0
	s_or_b32 s8, s12, 0x70000
	s_waitcnt vmcnt(0)
; __device__ __forceinline__ float softplusf_(float x) { return x > 20.f ? x : log1pf(expf(x)); }
; __device__ __forceinline__ const float* argf(int i) { return (const float*)kargs()[i]; }
; __device__ __forceinline__ void lru_job(const bf16_t* P, bf16_t* Y, int l, int b, int kb, LAS float* lds, int wave_s) {
;     ...
;     const int j = tid & 63, tg = tid >> 6, ch = kb * 64 + j;
;     typedef float f32x2_t __attribute__((ext_vector_type(2)));
;     f32x2_t wax[64];
;     { const float* wap = argf(15) + l * 16384; const float* wxp = argf(17) + l * 16384;
; #pragma unroll
;       for (int i = 0; i < 64; ++i) { wax[i].x = wap[(kb * 64 + i) * 64 + j]; wax[i].y = wxp[(kb * 64 + i) * 64 + j]; } }
;     const float ba = argf(16)[l * 256 + ch], bx = argf(18)[l * 256 + ch], spl = softplusf_(-argf(19)[l * 256 + ch]);
	v_cndmask_b32_e32 v174, 0, v175, vcc
	v_cmp_lt_i32_e32 vcc, 1, v179
	v_or3_b32 v175, v181, v180, s4
	v_mov_b32_e32 v184, v207
	v_cndmask_b32_e32 v178, 0, v176, vcc
	v_cmp_lt_i32_e32 vcc, 0, v179
	v_add_u32_e32 v176, 0, v134
	v_or_b32_e32 v134, v181, v134
	v_cndmask_b32_e32 v182, 0, v177, vcc
	v_and_b32_e32 v177, 0x3fffffc0, v135
	v_lshl_add_u32 v177, v177, 2, v176
	v_cmp_gt_i32_e32 vcc, 64, v135
	v_lshl_add_u32 v179, v179, 8, v176
	v_add_u32_e32 v180, 0, v134
	v_add_u32_e32 v181, 0, v181
	v_mov_b32_e32 v135, 0
	v_mov_b32_e32 v200, v196
	v_mov_b32_e32 v193, v197
	v_mov_b32_e32 v188, v202
	v_mov_b32_e32 v203, v195
	v_mov_b32_e32 v208, v190
	v_mov_b32_e32 v210, v189
	v_mov_b32_e32 v214, v186
	v_mbcnt_lo_u32_b32 v101, -1, 0
	v_mbcnt_hi_u32_b32 v101, -1, v101
	v_and_b32_e32 v102, 15, v101
	v_lshrrev_b32_e32 v103, 4, v101
	s_lshr_b32 s4, s67, 6
	s_and_b32 s5, s4, 3
	s_lshr_b32 s4, s4, 2
	s_lshl_b32 s6, s5, 4
	s_lshl_b32 s7, s4, 5
	v_add_u32_e32 v104, s6, v102
	v_lshlrev_b32_e32 v105, 2, v104
	ds_bpermute_b32 v96, v105, v132
	ds_bpermute_b32 v97, v105, v133
	ds_bpermute_b32 v98, v105, v39
	v_add_u32_e32 v99, s7, v102
	v_lshlrev_b32_e32 v99, 8, v99
	v_lshl_add_u32 v99, v103, 6, v99
	v_lshl_add_u32 v100, v103, 2, s7
	v_lshlrev_b32_e32 v100, 8, v100
	v_add_u32_e32 v100, v100, v105
	v_lshlrev_b32_e32 v106, 12, v103
	v_lshl_add_u32 v106, v102, 2, v106
	s_load_dwordx2 s[10:11], s[0:1], 0x78
	s_lshl_b32 s4, s70, 14
	s_lshl_b32 s6, s5, 6
	s_add_u32 s4, s4, s6
	s_add_u32 s4, s4, 0x10000
	s_waitcnt lgkmcnt(0)
	s_add_u32 s10, s10, s4
	s_addc_u32 s11, s11, 0
	s_nop 4
	global_load_dword v0, v106, s[10:11] offset:0
	global_load_dword v1, v106, s[10:11] offset:256
	global_load_dword v2, v106, s[10:11] offset:512
	global_load_dword v3, v106, s[10:11] offset:768
	global_load_dword v4, v106, s[10:11] offset:1024
	global_load_dword v5, v106, s[10:11] offset:1280
	global_load_dword v6, v106, s[10:11] offset:1536
	global_load_dword v7, v106, s[10:11] offset:1792
	global_load_dword v8, v106, s[10:11] offset:2048
	global_load_dword v9, v106, s[10:11] offset:2304
	global_load_dword v10, v106, s[10:11] offset:2560
	global_load_dword v11, v106, s[10:11] offset:2816
	global_load_dword v12, v106, s[10:11] offset:3072
	global_load_dword v13, v106, s[10:11] offset:3328
	global_load_dword v14, v106, s[10:11] offset:3584
	global_load_dword v15, v106, s[10:11] offset:3840
	s_load_dwordx2 s[10:11], s[0:1], 0x88
	s_waitcnt lgkmcnt(0)
	s_add_u32 s10, s10, s4
	s_addc_u32 s11, s11, 0
	s_nop 4
	global_load_dword v16, v106, s[10:11] offset:0
	global_load_dword v17, v106, s[10:11] offset:256
	global_load_dword v18, v106, s[10:11] offset:512
	global_load_dword v19, v106, s[10:11] offset:768
	global_load_dword v20, v106, s[10:11] offset:1024
	global_load_dword v21, v106, s[10:11] offset:1280
	global_load_dword v22, v106, s[10:11] offset:1536
	global_load_dword v23, v106, s[10:11] offset:1792
	global_load_dword v24, v106, s[10:11] offset:2048
	global_load_dword v25, v106, s[10:11] offset:2304
	global_load_dword v26, v106, s[10:11] offset:2560
	global_load_dword v27, v106, s[10:11] offset:2816
	global_load_dword v28, v106, s[10:11] offset:3072
	global_load_dword v29, v106, s[10:11] offset:3328
	global_load_dword v30, v106, s[10:11] offset:3584
	global_load_dword v31, v106, s[10:11] offset:3840
	s_waitcnt vmcnt(0)
	s_branch .LBB0_953

; #define LAS __attribute__((address_space(3)))
; __device__ __forceinline__ void lru_job(const bf16_t* P, bf16_t* Y, int l, int b, int kb, LAS float* lds, int wave_s) {
;     ...
;         for (int tt = 0; tt < 8; ++tt) { const int t = tg * 8 + tt; f32x2_t dd = {ba, bx};
; #pragma unroll
;             for (int i4 = 0; i4 < 16; ++i4) { const f32x4 xv = *(const LAS f32x4*)(XC + t * 64 + 4 * i4);
; #pragma unroll
;                 for (int q = 0; q < 4; ++q) { const f32x2_t xb = {xv[q], xv[q]}; dd = __builtin_elementwise_fma(xb, wax[4 * i4 + q], dd); } }
.LBB0_955:
	ds_read_b128 v[40:43], v99
	ds_read_b128 v[56:59], v99 offset:4096
	ds_read_b128 v[44:47], v99 offset:16
	ds_read_b128 v[60:63], v99 offset:4112
	ds_read_b128 v[48:51], v99 offset:32
	ds_read_b128 v[64:67], v99 offset:4128
	ds_read_b128 v[52:55], v99 offset:48
	ds_read_b128 v[68:71], v99 offset:4144
	ds_read_b32 v88, v100
	ds_read_b32 v89, v100 offset:256
	ds_read_b32 v90, v100 offset:512
	ds_read_b32 v91, v100 offset:768
	ds_read_b32 v92, v100 offset:4096
	ds_read_b32 v93, v100 offset:4352
	ds_read_b32 v94, v100 offset:4608
	ds_read_b32 v95, v100 offset:4864
	v_mov_b32_e32 v72, v96
	v_mov_b32_e32 v73, v96
	v_mov_b32_e32 v74, v96
	v_mov_b32_e32 v75, v96
	v_mov_b32_e32 v76, v97
	v_mov_b32_e32 v77, v97
	v_mov_b32_e32 v78, v97
	v_mov_b32_e32 v79, v97
	v_mov_b32_e32 v80, v96
	v_mov_b32_e32 v81, v96
	v_mov_b32_e32 v82, v96
	v_mov_b32_e32 v83, v96
	v_mov_b32_e32 v84, v97
	v_mov_b32_e32 v85, v97
	v_mov_b32_e32 v86, v97
	v_mov_b32_e32 v87, v97
	s_waitcnt lgkmcnt(14)
	s_nop 1
	v_mfma_f32_16x16x4_f32 v[72:75], v40, v0, v[72:75]
	v_mfma_f32_16x16x4_f32 v[76:79], v40, v16, v[76:79]
	v_mfma_f32_16x16x4_f32 v[80:83], v56, v0, v[80:83]
	v_mfma_f32_16x16x4_f32 v[84:87], v56, v16, v[84:87]
	v_mfma_f32_16x16x4_f32 v[72:75], v41, v1, v[72:75]
	v_mfma_f32_16x16x4_f32 v[76:79], v41, v17, v[76:79]
	v_mfma_f32_16x16x4_f32 v[80:83], v57, v1, v[80:83]
	v_mfma_f32_16x16x4_f32 v[84:87], v57, v17, v[84:87]
	v_mfma_f32_16x16x4_f32 v[72:75], v42, v2, v[72:75]
	v_mfma_f32_16x16x4_f32 v[76:79], v42, v18, v[76:79]
	v_mfma_f32_16x16x4_f32 v[80:83], v58, v2, v[80:83]
	v_mfma_f32_16x16x4_f32 v[84:87], v58, v18, v[84:87]
	v_mfma_f32_16x16x4_f32 v[72:75], v43, v3, v[72:75]
	v_mfma_f32_16x16x4_f32 v[76:79], v43, v19, v[76:79]
	v_mfma_f32_16x16x4_f32 v[80:83], v59, v3, v[80:83]
	v_mfma_f32_16x16x4_f32 v[84:87], v59, v19, v[84:87]
	s_waitcnt lgkmcnt(12)
	v_mfma_f32_16x16x4_f32 v[72:75], v44, v4, v[72:75]
	v_mfma_f32_16x16x4_f32 v[76:79], v44, v20, v[76:79]
	v_mfma_f32_16x16x4_f32 v[80:83], v60, v4, v[80:83]
	v_mfma_f32_16x16x4_f32 v[84:87], v60, v20, v[84:87]
	v_mfma_f32_16x16x4_f32 v[72:75], v45, v5, v[72:75]
	v_mfma_f32_16x16x4_f32 v[76:79], v45, v21, v[76:79]
	v_mfma_f32_16x16x4_f32 v[80:83], v61, v5, v[80:83]
	v_mfma_f32_16x16x4_f32 v[84:87], v61, v21, v[84:87]
	v_mfma_f32_16x16x4_f32 v[72:75], v46, v6, v[72:75]
	v_mfma_f32_16x16x4_f32 v[76:79], v46, v22, v[76:79]
	v_mfma_f32_16x16x4_f32 v[80:83], v62, v6, v[80:83]
	v_mfma_f32_16x16x4_f32 v[84:87], v62, v22, v[84:87]
	v_mfma_f32_16x16x4_f32 v[72:75], v47, v7, v[72:75]
	v_mfma_f32_16x16x4_f32 v[76:79], v47, v23, v[76:79]
	v_mfma_f32_16x16x4_f32 v[80:83], v63, v7, v[80:83]
	v_mfma_f32_16x16x4_f32 v[84:87], v63, v23, v[84:87]
	s_waitcnt lgkmcnt(10)
	v_mfma_f32_16x16x4_f32 v[72:75], v48, v8, v[72:75]
	v_mfma_f32_16x16x4_f32 v[76:79], v48, v24, v[76:79]
	v_mfma_f32_16x16x4_f32 v[80:83], v64, v8, v[80:83]
	v_mfma_f32_16x16x4_f32 v[84:87], v64, v24, v[84:87]
	v_mfma_f32_16x16x4_f32 v[72:75], v49, v9, v[72:75]
	v_mfma_f32_16x16x4_f32 v[76:79], v49, v25, v[76:79]
	v_mfma_f32_16x16x4_f32 v[80:83], v65, v9, v[80:83]
	v_mfma_f32_16x16x4_f32 v[84:87], v65, v25, v[84:87]
	v_mfma_f32_16x16x4_f32 v[72:75], v50, v10, v[72:75]
	v_mfma_f32_16x16x4_f32 v[76:79], v50, v26, v[76:79]
	v_mfma_f32_16x16x4_f32 v[80:83], v66, v10, v[80:83]
	v_mfma_f32_16x16x4_f32 v[84:87], v66, v26, v[84:87]
	v_mfma_f32_16x16x4_f32 v[72:75], v51, v11, v[72:75]
	v_mfma_f32_16x16x4_f32 v[76:79], v51, v27, v[76:79]
	v_mfma_f32_16x16x4_f32 v[80:83], v67, v11, v[80:83]
	v_mfma_f32_16x16x4_f32 v[84:87], v67, v27, v[84:87]
	s_waitcnt lgkmcnt(8)
	v_mfma_f32_16x16x4_f32 v[72:75], v52, v12, v[72:75]
	v_mfma_f32_16x16x4_f32 v[76:79], v52, v28, v[76:79]
	v_mfma_f32_16x16x4_f32 v[80:83], v68, v12, v[80:83]
	v_mfma_f32_16x16x4_f32 v[84:87], v68, v28, v[84:87]
	v_mfma_f32_16x16x4_f32 v[72:75], v53, v13, v[72:75]
	v_mfma_f32_16x16x4_f32 v[76:79], v53, v29, v[76:79]
	v_mfma_f32_16x16x4_f32 v[80:83], v69, v13, v[80:83]
	v_mfma_f32_16x16x4_f32 v[84:87], v69, v29, v[84:87]
	v_mfma_f32_16x16x4_f32 v[72:75], v54, v14, v[72:75]
	v_mfma_f32_16x16x4_f32 v[76:79], v54, v30, v[76:79]
	v_mfma_f32_16x16x4_f32 v[80:83], v70, v14, v[80:83]
	v_mfma_f32_16x16x4_f32 v[84:87], v70, v30, v[84:87]
	v_mfma_f32_16x16x4_f32 v[72:75], v55, v15, v[72:75]
	v_mfma_f32_16x16x4_f32 v[76:79], v55, v31, v[76:79]
	v_mfma_f32_16x16x4_f32 v[80:83], v71, v15, v[80:83]
	v_mfma_f32_16x16x4_f32 v[84:87], v71, v31, v[84:87]
	s_waitcnt lgkmcnt(0)
; __device__ __forceinline__ float sigmoidf_(float x) { return __builtin_amdgcn_rcpf(1.f + __expf(-x)); }
; __device__ __forceinline__ void lru_job(const bf16_t* P, bf16_t* Y, int l, int b, int kb, LAS float* lds, int wave_s) {
;     ...
;             const float rg = sigmoidf_(dd.x), ig = sigmoidf_(dd.y);
;             const float la = -8.f * rg * spl;
;             const float av = __expf(la);
;             Aa[t * 64 + j] = av;
;             Uu[t * 64 + j] = sqrtf(fmaxf(1.f - av * av, 0.f)) * (ig * XC[t * 64 + j]); }
	s_nop 7
	s_nop 3
	v_mul_f32_e32 v101, 0xbfb8aa3b, v72
	v_exp_f32_e32 v101, v101
	v_mul_f32_e32 v102, 0xbfb8aa3b, v76
	v_exp_f32_e32 v102, v102
	s_mov_b32 s4, 0xf800000
	v_add_f32_e32 v101, 1.0, v101
	v_rcp_f32_e32 v101, v101
	v_add_f32_e32 v102, 1.0, v102
	v_rcp_f32_e32 v102, v102
	s_nop 0
	v_mul_f32_e32 v101, 0xc1000000, v101
	v_mul_f32_e32 v101, v98, v101
	v_mul_f32_e32 v101, 0x3fb8aa3b, v101
	v_exp_f32_e32 v101, v101
	v_mul_f32_e32 v102, v88, v102
	v_fma_f32 v103, -v101, v101, 1.0
	v_max_f32_e32 v103, 0, v103
	v_cmp_gt_f32_e64 s[4:5], s4, v103
	v_mul_f32_e32 v104, 0x4f800000, v103
	s_nop 0
	v_cndmask_b32_e64 v103, v103, v104, s[4:5]
	v_sqrt_f32_e32 v104, v103
	s_nop 0
	v_add_u32_e32 v105, -1, v104
	v_fma_f32 v106, -v105, v104, v103
	v_cmp_ge_f32_e64 s[6:7], 0, v106
	v_add_u32_e32 v106, 1, v104
	s_nop 0
	v_cndmask_b32_e64 v105, v104, v105, s[6:7]
	v_fma_f32 v104, -v106, v104, v103
	v_cmp_lt_f32_e64 s[6:7], 0, v104
	s_nop 1
	v_cndmask_b32_e64 v104, v105, v106, s[6:7]
	v_mul_f32_e32 v105, 0x37800000, v104
	v_cndmask_b32_e64 v104, v104, v105, s[4:5]
	v_mov_b32_e32 v105, 0x260
	v_cmp_class_f32_e64 s[4:5], v103, v105
	s_nop 1
	v_cndmask_b32_e64 v103, v104, v103, s[4:5]
	v_mul_f32_e32 v102, v102, v103
	ds_write2st64_b32 v100, v101, v102 offset0:64 offset1:128
	v_mul_f32_e32 v101, 0xbfb8aa3b, v73
	v_exp_f32_e32 v101, v101
	v_mul_f32_e32 v102, 0xbfb8aa3b, v77
	v_exp_f32_e32 v102, v102
	s_mov_b32 s4, 0xf800000
	v_add_f32_e32 v101, 1.0, v101
	v_rcp_f32_e32 v101, v101
	v_add_f32_e32 v102, 1.0, v102
	v_rcp_f32_e32 v102, v102
	s_nop 0
	v_mul_f32_e32 v101, 0xc1000000, v101
	v_mul_f32_e32 v101, v98, v101
	v_mul_f32_e32 v101, 0x3fb8aa3b, v101
	v_exp_f32_e32 v101, v101
	v_mul_f32_e32 v102, v89, v102
	v_fma_f32 v103, -v101, v101, 1.0
	v_max_f32_e32 v103, 0, v103
	v_cmp_gt_f32_e64 s[4:5], s4, v103
	v_mul_f32_e32 v104, 0x4f800000, v103
	s_nop 0
	v_cndmask_b32_e64 v103, v103, v104, s[4:5]
	v_sqrt_f32_e32 v104, v103
	s_nop 0
	v_add_u32_e32 v105, -1, v104
	v_fma_f32 v106, -v105, v104, v103
	v_cmp_ge_f32_e64 s[6:7], 0, v106
	v_add_u32_e32 v106, 1, v104
	s_nop 0
	v_cndmask_b32_e64 v105, v104, v105, s[6:7]
	v_fma_f32 v104, -v106, v104, v103
	v_cmp_lt_f32_e64 s[6:7], 0, v104
	s_nop 1
	v_cndmask_b32_e64 v104, v105, v106, s[6:7]
	v_mul_f32_e32 v105, 0x37800000, v104
	v_cndmask_b32_e64 v104, v104, v105, s[4:5]
	v_mov_b32_e32 v105, 0x260
	v_cmp_class_f32_e64 s[4:5], v103, v105
	s_nop 1
	v_cndmask_b32_e64 v103, v104, v103, s[4:5]
	v_mul_f32_e32 v102, v102, v103
	ds_write2st64_b32 v100, v101, v102 offset0:65 offset1:129
	v_mul_f32_e32 v101, 0xbfb8aa3b, v74
	v_exp_f32_e32 v101, v101
	v_mul_f32_e32 v102, 0xbfb8aa3b, v78
	v_exp_f32_e32 v102, v102
	s_mov_b32 s4, 0xf800000
	v_add_f32_e32 v101, 1.0, v101
	v_rcp_f32_e32 v101, v101
	v_add_f32_e32 v102, 1.0, v102
	v_rcp_f32_e32 v102, v102
	s_nop 0
	v_mul_f32_e32 v101, 0xc1000000, v101
	v_mul_f32_e32 v101, v98, v101
	v_mul_f32_e32 v101, 0x3fb8aa3b, v101
	v_exp_f32_e32 v101, v101
	v_mul_f32_e32 v102, v90, v102
	v_fma_f32 v103, -v101, v101, 1.0
	v_max_f32_e32 v103, 0, v103
	v_cmp_gt_f32_e64 s[4:5], s4, v103
	v_mul_f32_e32 v104, 0x4f800000, v103
	s_nop 0
	v_cndmask_b32_e64 v103, v103, v104, s[4:5]
	v_sqrt_f32_e32 v104, v103
	s_nop 0
	v_add_u32_e32 v105, -1, v104
	v_fma_f32 v106, -v105, v104, v103
	v_cmp_ge_f32_e64 s[6:7], 0, v106
	v_add_u32_e32 v106, 1, v104
	s_nop 0
	v_cndmask_b32_e64 v105, v104, v105, s[6:7]
	v_fma_f32 v104, -v106, v104, v103
	v_cmp_lt_f32_e64 s[6:7], 0, v104
	s_nop 1
	v_cndmask_b32_e64 v104, v105, v106, s[6:7]
	v_mul_f32_e32 v105, 0x37800000, v104
	v_cndmask_b32_e64 v104, v104, v105, s[4:5]
	v_mov_b32_e32 v105, 0x260
	v_cmp_class_f32_e64 s[4:5], v103, v105
	s_nop 1
	v_cndmask_b32_e64 v103, v104, v103, s[4:5]
	v_mul_f32_e32 v102, v102, v103
	ds_write2st64_b32 v100, v101, v102 offset0:66 offset1:130
	v_mul_f32_e32 v101, 0xbfb8aa3b, v75
	v_exp_f32_e32 v101, v101
	v_mul_f32_e32 v102, 0xbfb8aa3b, v79
	v_exp_f32_e32 v102, v102
	s_mov_b32 s4, 0xf800000
	v_add_f32_e32 v101, 1.0, v101
	v_rcp_f32_e32 v101, v101
	v_add_f32_e32 v102, 1.0, v102
	v_rcp_f32_e32 v102, v102
	s_nop 0
	v_mul_f32_e32 v101, 0xc1000000, v101
	v_mul_f32_e32 v101, v98, v101
	v_mul_f32_e32 v101, 0x3fb8aa3b, v101
	v_exp_f32_e32 v101, v101
	v_mul_f32_e32 v102, v91, v102
	v_fma_f32 v103, -v101, v101, 1.0
	v_max_f32_e32 v103, 0, v103
	v_cmp_gt_f32_e64 s[4:5], s4, v103
	v_mul_f32_e32 v104, 0x4f800000, v103
	s_nop 0
	v_cndmask_b32_e64 v103, v103, v104, s[4:5]
	v_sqrt_f32_e32 v104, v103
	s_nop 0
	v_add_u32_e32 v105, -1, v104
	v_fma_f32 v106, -v105, v104, v103
	v_cmp_ge_f32_e64 s[6:7], 0, v106
	v_add_u32_e32 v106, 1, v104
	s_nop 0
	v_cndmask_b32_e64 v105, v104, v105, s[6:7]
	v_fma_f32 v104, -v106, v104, v103
	v_cmp_lt_f32_e64 s[6:7], 0, v104
	s_nop 1
	v_cndmask_b32_e64 v104, v105, v106, s[6:7]
	v_mul_f32_e32 v105, 0x37800000, v104
	v_cndmask_b32_e64 v104, v104, v105, s[4:5]
	v_mov_b32_e32 v105, 0x260
	v_cmp_class_f32_e64 s[4:5], v103, v105
	s_nop 1
	v_cndmask_b32_e64 v103, v104, v103, s[4:5]
	v_mul_f32_e32 v102, v102, v103
	ds_write2st64_b32 v100, v101, v102 offset0:67 offset1:131
	v_mul_f32_e32 v101, 0xbfb8aa3b, v80
	v_exp_f32_e32 v101, v101
	v_mul_f32_e32 v102, 0xbfb8aa3b, v84
	v_exp_f32_e32 v102, v102
	s_mov_b32 s4, 0xf800000
	v_add_f32_e32 v101, 1.0, v101
	v_rcp_f32_e32 v101, v101
	v_add_f32_e32 v102, 1.0, v102
	v_rcp_f32_e32 v102, v102
	s_nop 0
	v_mul_f32_e32 v101, 0xc1000000, v101
	v_mul_f32_e32 v101, v98, v101
	v_mul_f32_e32 v101, 0x3fb8aa3b, v101
	v_exp_f32_e32 v101, v101
	v_mul_f32_e32 v102, v92, v102
	v_fma_f32 v103, -v101, v101, 1.0
	v_max_f32_e32 v103, 0, v103
	v_cmp_gt_f32_e64 s[4:5], s4, v103
	v_mul_f32_e32 v104, 0x4f800000, v103
	s_nop 0
; __device__ __forceinline__ float sigmoidf_(float x) { return __builtin_amdgcn_rcpf(1.f + __expf(-x)); }
; __device__ __forceinline__ void lru_job(const bf16_t* P, bf16_t* Y, int l, int b, int kb, LAS float* lds, int wave_s) {
;     ...
;             const float rg = sigmoidf_(dd.x), ig = sigmoidf_(dd.y);
;             const float la = -8.f * rg * spl;
;             const float av = __expf(la);
;             Aa[t * 64 + j] = av;
;             Uu[t * 64 + j] = sqrtf(fmaxf(1.f - av * av, 0.f)) * (ig * XC[t * 64 + j]); }
;         __syncthreads();
	v_cndmask_b32_e64 v103, v103, v104, s[4:5]
	v_sqrt_f32_e32 v104, v103
	s_nop 0
	v_add_u32_e32 v105, -1, v104
	v_fma_f32 v106, -v105, v104, v103
	v_cmp_ge_f32_e64 s[6:7], 0, v106
	v_add_u32_e32 v106, 1, v104
	s_nop 0
	v_cndmask_b32_e64 v105, v104, v105, s[6:7]
	v_fma_f32 v104, -v106, v104, v103
	v_cmp_lt_f32_e64 s[6:7], 0, v104
	s_nop 1
	v_cndmask_b32_e64 v104, v105, v106, s[6:7]
	v_mul_f32_e32 v105, 0x37800000, v104
	v_cndmask_b32_e64 v104, v104, v105, s[4:5]
	v_mov_b32_e32 v105, 0x260
	v_cmp_class_f32_e64 s[4:5], v103, v105
	s_nop 1
	v_cndmask_b32_e64 v103, v104, v103, s[4:5]
	v_mul_f32_e32 v102, v102, v103
	ds_write2st64_b32 v100, v101, v102 offset0:80 offset1:144
	v_mul_f32_e32 v101, 0xbfb8aa3b, v81
	v_exp_f32_e32 v101, v101
	v_mul_f32_e32 v102, 0xbfb8aa3b, v85
	v_exp_f32_e32 v102, v102
	s_mov_b32 s4, 0xf800000
	v_add_f32_e32 v101, 1.0, v101
	v_rcp_f32_e32 v101, v101
	v_add_f32_e32 v102, 1.0, v102
	v_rcp_f32_e32 v102, v102
	s_nop 0
	v_mul_f32_e32 v101, 0xc1000000, v101
	v_mul_f32_e32 v101, v98, v101
	v_mul_f32_e32 v101, 0x3fb8aa3b, v101
	v_exp_f32_e32 v101, v101
	v_mul_f32_e32 v102, v93, v102
	v_fma_f32 v103, -v101, v101, 1.0
	v_max_f32_e32 v103, 0, v103
	v_cmp_gt_f32_e64 s[4:5], s4, v103
	v_mul_f32_e32 v104, 0x4f800000, v103
	s_nop 0
	v_cndmask_b32_e64 v103, v103, v104, s[4:5]
	v_sqrt_f32_e32 v104, v103
	s_nop 0
	v_add_u32_e32 v105, -1, v104
	v_fma_f32 v106, -v105, v104, v103
	v_cmp_ge_f32_e64 s[6:7], 0, v106
	v_add_u32_e32 v106, 1, v104
	s_nop 0
	v_cndmask_b32_e64 v105, v104, v105, s[6:7]
	v_fma_f32 v104, -v106, v104, v103
	v_cmp_lt_f32_e64 s[6:7], 0, v104
	s_nop 1
	v_cndmask_b32_e64 v104, v105, v106, s[6:7]
	v_mul_f32_e32 v105, 0x37800000, v104
	v_cndmask_b32_e64 v104, v104, v105, s[4:5]
	v_mov_b32_e32 v105, 0x260
	v_cmp_class_f32_e64 s[4:5], v103, v105
	s_nop 1
	v_cndmask_b32_e64 v103, v104, v103, s[4:5]
	v_mul_f32_e32 v102, v102, v103
	ds_write2st64_b32 v100, v101, v102 offset0:81 offset1:145
	v_mul_f32_e32 v101, 0xbfb8aa3b, v82
	v_exp_f32_e32 v101, v101
	v_mul_f32_e32 v102, 0xbfb8aa3b, v86
	v_exp_f32_e32 v102, v102
	s_mov_b32 s4, 0xf800000
	v_add_f32_e32 v101, 1.0, v101
	v_rcp_f32_e32 v101, v101
	v_add_f32_e32 v102, 1.0, v102
	v_rcp_f32_e32 v102, v102
	s_nop 0
	v_mul_f32_e32 v101, 0xc1000000, v101
	v_mul_f32_e32 v101, v98, v101
	v_mul_f32_e32 v101, 0x3fb8aa3b, v101
	v_exp_f32_e32 v101, v101
	v_mul_f32_e32 v102, v94, v102
	v_fma_f32 v103, -v101, v101, 1.0
	v_max_f32_e32 v103, 0, v103
	v_cmp_gt_f32_e64 s[4:5], s4, v103
	v_mul_f32_e32 v104, 0x4f800000, v103
	s_nop 0
	v_cndmask_b32_e64 v103, v103, v104, s[4:5]
	v_sqrt_f32_e32 v104, v103
	s_nop 0
	v_add_u32_e32 v105, -1, v104
	v_fma_f32 v106, -v105, v104, v103
	v_cmp_ge_f32_e64 s[6:7], 0, v106
	v_add_u32_e32 v106, 1, v104
	s_nop 0
	v_cndmask_b32_e64 v105, v104, v105, s[6:7]
	v_fma_f32 v104, -v106, v104, v103
	v_cmp_lt_f32_e64 s[6:7], 0, v104
	s_nop 1
	v_cndmask_b32_e64 v104, v105, v106, s[6:7]
	v_mul_f32_e32 v105, 0x37800000, v104
	v_cndmask_b32_e64 v104, v104, v105, s[4:5]
	v_mov_b32_e32 v105, 0x260
	v_cmp_class_f32_e64 s[4:5], v103, v105
	s_nop 1
	v_cndmask_b32_e64 v103, v104, v103, s[4:5]
	v_mul_f32_e32 v102, v102, v103
	ds_write2st64_b32 v100, v101, v102 offset0:82 offset1:146
	v_mul_f32_e32 v101, 0xbfb8aa3b, v83
	v_exp_f32_e32 v101, v101
	v_mul_f32_e32 v102, 0xbfb8aa3b, v87
	v_exp_f32_e32 v102, v102
	s_mov_b32 s4, 0xf800000
	v_add_f32_e32 v101, 1.0, v101
	v_rcp_f32_e32 v101, v101
	v_add_f32_e32 v102, 1.0, v102
	v_rcp_f32_e32 v102, v102
	s_nop 0
	v_mul_f32_e32 v101, 0xc1000000, v101
	v_mul_f32_e32 v101, v98, v101
	v_mul_f32_e32 v101, 0x3fb8aa3b, v101
	v_exp_f32_e32 v101, v101
	v_mul_f32_e32 v102, v95, v102
	v_fma_f32 v103, -v101, v101, 1.0
	v_max_f32_e32 v103, 0, v103
	v_cmp_gt_f32_e64 s[4:5], s4, v103
	v_mul_f32_e32 v104, 0x4f800000, v103
	s_nop 0
	v_cndmask_b32_e64 v103, v103, v104, s[4:5]
	v_sqrt_f32_e32 v104, v103
	s_nop 0
	v_add_u32_e32 v105, -1, v104
	v_fma_f32 v106, -v105, v104, v103
	v_cmp_ge_f32_e64 s[6:7], 0, v106
	v_add_u32_e32 v106, 1, v104
	s_nop 0
	v_cndmask_b32_e64 v105, v104, v105, s[6:7]
	v_fma_f32 v104, -v106, v104, v103
	v_cmp_lt_f32_e64 s[6:7], 0, v104
	s_nop 1
	v_cndmask_b32_e64 v104, v105, v106, s[6:7]
	v_mul_f32_e32 v105, 0x37800000, v104
	v_cndmask_b32_e64 v104, v104, v105, s[4:5]
	v_mov_b32_e32 v105, 0x260
	v_cmp_class_f32_e64 s[4:5], v103, v105
	s_nop 1
	v_cndmask_b32_e64 v103, v104, v103, s[4:5]
	v_mul_f32_e32 v102, v102, v103
	ds_write2st64_b32 v100, v101, v102 offset0:83 offset1:147
	s_waitcnt lgkmcnt(0)
	s_barrier
	s_and_saveexec_b64 s[4:5], vcc
	s_cbranch_execz .LBB0_952
; __device__ __forceinline__ void lru_job(const bf16_t* P, bf16_t* Y, int l, int b, int kb, LAS float* lds, int wave_s) {
;     ...
;         if (tid < 64) {
;             for (int tb = 0; tb < TC; tb += 8) { float av[8], uv[8];
; #pragma unroll
;                 for (int k = 0; k < 8; ++k) { av[k] = Aa[(tb + k) * 64 + j]; uv[k] = Uu[(tb + k) * 64 + j]; }
; #pragma unroll
;                 for (int k = 0; k < 8; ++k) { hs = av[k] * hs + uv[k]; Hh[(tb + k) * 64 + j] = hs; } }
;         }
	ds_read2st64_b32 v[216:217], v176 offset0:128 offset1:129
	ds_read2st64_b32 v[218:219], v176 offset0:64 offset1:65
	ds_read2st64_b32 v[220:221], v176 offset0:66 offset1:67
	ds_read2st64_b32 v[222:223], v176 offset0:68 offset1:69
	ds_read2st64_b32 v[224:225], v176 offset0:70 offset1:71
	ds_read2st64_b32 v[226:227], v176 offset0:130 offset1:131
	ds_read2st64_b32 v[228:229], v176 offset0:132 offset1:133
	ds_read2st64_b32 v[230:231], v176 offset0:134 offset1:135
	s_waitcnt lgkmcnt(6)
	v_fma_f32 v134, v135, v218, v216
	v_fmac_f32_e32 v217, v134, v219
	ds_write2st64_b32 v176, v134, v217 offset0:192 offset1:193
	s_waitcnt lgkmcnt(3)
	v_fma_f32 v134, v217, v220, v226
	v_fmac_f32_e32 v227, v134, v221
	ds_write2st64_b32 v176, v134, v227 offset0:194 offset1:195
	s_waitcnt lgkmcnt(3)
	v_fma_f32 v134, v227, v222, v228
	v_fmac_f32_e32 v229, v134, v223
	ds_write2st64_b32 v176, v134, v229 offset0:196 offset1:197
	s_waitcnt lgkmcnt(3)
	v_fma_f32 v134, v229, v224, v230
	v_fmac_f32_e32 v231, v134, v225
	ds_write2st64_b32 v176, v134, v231 offset0:198 offset1:199
	ds_read2st64_b32 v[134:135], v176 offset0:136 offset1:137
	ds_read2st64_b32 v[216:217], v176 offset0:72 offset1:73
	ds_read2st64_b32 v[218:219], v176 offset0:74 offset1:75
	ds_read2st64_b32 v[220:221], v176 offset0:76 offset1:77
	ds_read2st64_b32 v[222:223], v176 offset0:78 offset1:79
	ds_read2st64_b32 v[224:225], v176 offset0:138 offset1:139
	ds_read2st64_b32 v[226:227], v176 offset0:140 offset1:141
	ds_read2st64_b32 v[228:229], v176 offset0:142 offset1:143
	s_waitcnt lgkmcnt(6)
	v_fma_f32 v134, v231, v216, v134
	v_fmac_f32_e32 v135, v134, v217
	ds_write2st64_b32 v176, v134, v135 offset0:200 offset1:201
	s_waitcnt lgkmcnt(3)
	v_fma_f32 v134, v135, v218, v224
	v_fmac_f32_e32 v225, v134, v219
	ds_write2st64_b32 v176, v134, v225 offset0:202 offset1:203
	s_waitcnt lgkmcnt(3)
	v_fma_f32 v134, v225, v220, v226
	v_fmac_f32_e32 v227, v134, v221
	ds_write2st64_b32 v176, v134, v227 offset0:204 offset1:205
	s_waitcnt lgkmcnt(3)
	v_fma_f32 v134, v227, v222, v228
	v_fmac_f32_e32 v229, v134, v223
	ds_write2st64_b32 v176, v134, v229 offset0:206 offset1:207
	ds_read2st64_b32 v[134:135], v176 offset0:144 offset1:145
	ds_read2st64_b32 v[216:217], v176 offset0:80 offset1:81
	ds_read2st64_b32 v[218:219], v176 offset0:82 offset1:83
	ds_read2st64_b32 v[220:221], v176 offset0:84 offset1:85
	ds_read2st64_b32 v[222:223], v176 offset0:86 offset1:87
	ds_read2st64_b32 v[224:225], v176 offset0:146 offset1:147
	ds_read2st64_b32 v[226:227], v176 offset0:148 offset1:149
	ds_read2st64_b32 v[230:231], v176 offset0:150 offset1:151
	s_waitcnt lgkmcnt(6)
	v_fma_f32 v134, v229, v216, v134
	v_fmac_f32_e32 v135, v134, v217
	ds_write2st64_b32 v176, v134, v135 offset0:208 offset1:209
	s_waitcnt lgkmcnt(3)
	v_fma_f32 v134, v135, v218, v224
	v_fmac_f32_e32 v225, v134, v219
	ds_write2st64_b32 v176, v134, v225 offset0:210 offset1:211
	s_waitcnt lgkmcnt(3)
	v_fma_f32 v134, v225, v220, v226
	v_fmac_f32_e32 v227, v134, v221
	ds_write2st64_b32 v176, v134, v227 offset0:212 offset1:213
	s_waitcnt lgkmcnt(3)
	v_fma_f32 v134, v227, v222, v230
	v_fmac_f32_e32 v231, v134, v223
	ds_write2st64_b32 v176, v134, v231 offset0:214 offset1:215
	ds_read2st64_b32 v[134:135], v176 offset0:152 offset1:153
	ds_read2st64_b32 v[216:217], v176 offset0:88 offset1:89
	ds_read2st64_b32 v[218:219], v176 offset0:90 offset1:91
	ds_read2st64_b32 v[220:221], v176 offset0:92 offset1:93
	ds_read2st64_b32 v[222:223], v176 offset0:94 offset1:95
	ds_read2st64_b32 v[224:225], v176 offset0:154 offset1:155
	ds_read2st64_b32 v[226:227], v176 offset0:156 offset1:157
	ds_read2st64_b32 v[228:229], v176 offset0:158 offset1:159
	s_waitcnt lgkmcnt(6)
	v_fma_f32 v134, v231, v216, v134
	v_fmac_f32_e32 v135, v134, v217
	ds_write2st64_b32 v176, v134, v135 offset0:216 offset1:217
	s_waitcnt lgkmcnt(3)
	v_fma_f32 v134, v135, v218, v224
	v_fmac_f32_e32 v225, v134, v219
	ds_write2st64_b32 v176, v134, v225 offset0:218 offset1:219
	s_waitcnt lgkmcnt(3)
	v_fma_f32 v134, v225, v220, v226
	v_fmac_f32_e32 v227, v134, v221
	ds_write2st64_b32 v176, v134, v227 offset0:220 offset1:221
	s_waitcnt lgkmcnt(3)
; __device__ __forceinline__ void lru_job(const bf16_t* P, bf16_t* Y, int l, int b, int kb, LAS float* lds, int wave_s) {
;     ...
;         if (tid < 64) {
;             for (int tb = 0; tb < TC; tb += 8) { float av[8], uv[8];
; #pragma unroll
;                 for (int k = 0; k < 8; ++k) { av[k] = Aa[(tb + k) * 64 + j]; uv[k] = Uu[(tb + k) * 64 + j]; }
; #pragma unroll
;                 for (int k = 0; k < 8; ++k) { hs = av[k] * hs + uv[k]; Hh[(tb + k) * 64 + j] = hs; } }
;         }
	v_fma_f32 v134, v227, v222, v228
	v_fmac_f32_e32 v229, v134, v223
	ds_write2st64_b32 v176, v134, v229 offset0:222 offset1:223
	ds_read2st64_b32 v[134:135], v176 offset0:160 offset1:161
	ds_read2st64_b32 v[216:217], v176 offset0:96 offset1:97
	ds_read2st64_b32 v[218:219], v176 offset0:98 offset1:99
	ds_read2st64_b32 v[220:221], v176 offset0:100 offset1:101
	ds_read2st64_b32 v[222:223], v176 offset0:102 offset1:103
	ds_read2st64_b32 v[224:225], v176 offset0:162 offset1:163
	ds_read2st64_b32 v[226:227], v176 offset0:164 offset1:165
	ds_read2st64_b32 v[230:231], v176 offset0:166 offset1:167
	s_waitcnt lgkmcnt(6)
	v_fma_f32 v134, v229, v216, v134
	v_fmac_f32_e32 v135, v134, v217
	ds_write2st64_b32 v176, v134, v135 offset0:224 offset1:225
	s_waitcnt lgkmcnt(3)
	v_fma_f32 v134, v135, v218, v224
	v_fmac_f32_e32 v225, v134, v219
	ds_write2st64_b32 v176, v134, v225 offset0:226 offset1:227
	s_waitcnt lgkmcnt(3)
	v_fma_f32 v134, v225, v220, v226
	v_fmac_f32_e32 v227, v134, v221
	ds_write2st64_b32 v176, v134, v227 offset0:228 offset1:229
	s_waitcnt lgkmcnt(3)
	v_fma_f32 v134, v227, v222, v230
	v_fmac_f32_e32 v231, v134, v223
	ds_write2st64_b32 v176, v134, v231 offset0:230 offset1:231
	ds_read2st64_b32 v[134:135], v176 offset0:168 offset1:169
	ds_read2st64_b32 v[216:217], v176 offset0:104 offset1:105
	ds_read2st64_b32 v[218:219], v176 offset0:106 offset1:107
	ds_read2st64_b32 v[220:221], v176 offset0:108 offset1:109
	ds_read2st64_b32 v[222:223], v176 offset0:110 offset1:111
	ds_read2st64_b32 v[224:225], v176 offset0:170 offset1:171
	ds_read2st64_b32 v[226:227], v176 offset0:172 offset1:173
	ds_read2st64_b32 v[228:229], v176 offset0:174 offset1:175
	s_waitcnt lgkmcnt(6)
	v_fma_f32 v134, v231, v216, v134
	v_fmac_f32_e32 v135, v134, v217
	ds_write2st64_b32 v176, v134, v135 offset0:232 offset1:233
	s_waitcnt lgkmcnt(3)
	v_fma_f32 v134, v135, v218, v224
	v_fmac_f32_e32 v225, v134, v219
	ds_write2st64_b32 v176, v134, v225 offset0:234 offset1:235
	s_waitcnt lgkmcnt(3)
	v_fma_f32 v134, v225, v220, v226
	v_fmac_f32_e32 v227, v134, v221
	ds_write2st64_b32 v176, v134, v227 offset0:236 offset1:237
	s_waitcnt lgkmcnt(3)
	v_fma_f32 v134, v227, v222, v228
	v_fmac_f32_e32 v229, v134, v223
	ds_write2st64_b32 v176, v134, v229 offset0:238 offset1:239
	ds_read2st64_b32 v[134:135], v176 offset0:176 offset1:177
	ds_read2st64_b32 v[216:217], v176 offset0:112 offset1:113
	ds_read2st64_b32 v[218:219], v176 offset0:114 offset1:115
	ds_read2st64_b32 v[220:221], v176 offset0:116 offset1:117
	ds_read2st64_b32 v[222:223], v176 offset0:118 offset1:119
	ds_read2st64_b32 v[224:225], v176 offset0:178 offset1:179
	ds_read2st64_b32 v[226:227], v176 offset0:180 offset1:181
	ds_read2st64_b32 v[230:231], v176 offset0:182 offset1:183
	s_waitcnt lgkmcnt(6)
	v_fma_f32 v134, v229, v216, v134
	v_fmac_f32_e32 v135, v134, v217
	ds_write2st64_b32 v176, v134, v135 offset0:240 offset1:241
	s_waitcnt lgkmcnt(3)
	v_fma_f32 v134, v135, v218, v224
	v_fmac_f32_e32 v225, v134, v219
	ds_write2st64_b32 v176, v134, v225 offset0:242 offset1:243
	s_waitcnt lgkmcnt(3)
	v_fma_f32 v134, v225, v220, v226
	v_fmac_f32_e32 v227, v134, v221
	ds_write2st64_b32 v176, v134, v227 offset0:244 offset1:245
	s_waitcnt lgkmcnt(3)
	v_fma_f32 v134, v227, v222, v230
	v_fmac_f32_e32 v231, v134, v223
	ds_write2st64_b32 v176, v134, v231 offset0:246 offset1:247
	ds_read2st64_b32 v[216:217], v176 offset0:184 offset1:185
	ds_read2st64_b32 v[218:219], v176 offset0:120 offset1:121
	ds_read2st64_b32 v[220:221], v176 offset0:122 offset1:123
	ds_read2st64_b32 v[222:223], v176 offset0:124 offset1:125
	ds_read2st64_b32 v[224:225], v176 offset0:126 offset1:127
	ds_read2st64_b32 v[226:227], v176 offset0:186 offset1:187
	ds_read2st64_b32 v[228:229], v176 offset0:188 offset1:189
	ds_read2st64_b32 v[134:135], v176 offset0:190 offset1:191
	s_waitcnt lgkmcnt(6)
	v_fma_f32 v216, v231, v218, v216
	v_fmac_f32_e32 v217, v216, v219
	ds_write2st64_b32 v176, v216, v217 offset0:248 offset1:249
	s_waitcnt lgkmcnt(3)
	v_fma_f32 v216, v217, v220, v226
	v_fmac_f32_e32 v227, v216, v221
	ds_write2st64_b32 v176, v216, v227 offset0:250 offset1:251
	s_waitcnt lgkmcnt(3)
	v_fma_f32 v216, v227, v222, v228
	v_fmac_f32_e32 v229, v216, v223
	s_waitcnt lgkmcnt(2)
	v_fma_f32 v134, v229, v224, v134
	v_fmac_f32_e32 v135, v134, v225
	ds_write2st64_b32 v176, v216, v229 offset0:252 offset1:253
	ds_write2st64_b32 v176, v134, v135 offset0:254 offset1:255
	s_branch .LBB0_952
